# K-loop MFMAs reordered along a serpentine path (consecutive MFMAs share accumulator or one operand fragment); plus earlier SALU/epilogue/wait edits
# speedup vs baseline: 1.0094x; 1.0094x over previous
; __device__ __forceinline__ void finishSM(f32x16& p0, f32x16& p1, float alpha, float& l_reg, bf16x8& pa0, bf16x8& pa1, bf16x8& pa2, bf16x8& pa3) {
; #pragma unroll
;   for (int r = 0; r < 16; ++r) p1[r] = __builtin_amdgcn_exp2f(p1[r]);
;   float ps = 0;
; #pragma unroll
;   for (int r = 0; r < 16; ++r) ps += p0[r];
; #pragma unroll
;   for (int r = 0; r < 16; ++r) ps += p1[r];
;   { auto rr = __builtin_amdgcn_permlane32_swap(__float_as_uint(ps), __float_as_uint(ps), false, false);
;     ps = __uint_as_float(rr[0]) + __uint_as_float(rr[1]); }
;   l_reg = l_reg * alpha + ps;
;     ...
;   PK4(p0, 0, pa0); PK4(p0, 8, pa1); PK4(p1, 0, pa2); PK4(p1, 8, pa3);
;     ...
; }
; __device__ __forceinline__ void qkt(f32x16& p0, f32x16& p1, const bf16_t* Ks, const bf16x8* qr, int r32, int hi) {
;   p0 = f32x16{}; p1 = f32x16{};
; #pragma unroll
;   for (int d0 = 0; d0 < 8; ++d0) { int cb = (d0 * 16 + hi * 8) * 2;
;     bf16x8 b0 = *reinterpret_cast<const bf16x8*>((const char*)Ks + KSWZ(r32, cb));
;     bf16x8 b1 = *reinterpret_cast<const bf16x8*>((const char*)Ks + KSWZ(32 + r32, cb));
;     p0 = __builtin_amdgcn_mfma_f32_32x32x16_bf16(b0, qr[d0], p0, 0, 0, 0);
;     p1 = __builtin_amdgcn_mfma_f32_32x32x16_bf16(b1, qr[d0], p1, 0, 0, 0); }
; }
; __device__ __forceinline__ int v_st(int k, int c) { const int kk = (k & ~0xC) | ((k & 4) << 1) | ((k & 8) >> 1); return ((kk >> 3) * 4 + (c >> 5)) * 512 + ((kk & 7) * 32 + (c & 31)) * 2; }
; __device__ __forceinline__ int v_rd_base(int lane) { return ((lane & 3) << 3) | (((lane >> 2) & 3) << 6) | (((lane >> 4) & 1) << 5) | (((lane >> 5) & 1) << 8); }
; template <int OFF> __device__ __forceinline__ s16x4 tr_read(int vb) {
;   s16x4 r; asm volatile("ds_read_b64_tr_b16 %0, %1 offset:%2" : "=&v"(r) : "v"(vb), "i"(OFF) : "memory"); return r;
; }
; template <int D0> __device__ __forceinline__ void pv_one(f32x16& od, int vb, bf16x8 pa0, bf16x8 pa1, bf16x8 pa2, bf16x8 pa3) {
;   const s16x4 l0 = tr_read<v_rd_off(D0, 0, 0)>(vb), h0 = tr_read<v_rd_off(D0, 0, 1)>(vb), l1 = tr_read<v_rd_off(D0, 1, 0)>(vb), h1 = tr_read<v_rd_off(D0, 1, 1)>(vb);
;   const s16x4 l2 = tr_read<v_rd_off(D0, 2, 0)>(vb), h2 = tr_read<v_rd_off(D0, 2, 1)>(vb), l3 = tr_read<v_rd_off(D0, 3, 0)>(vb), h3 = tr_read<v_rd_off(D0, 3, 1)>(vb);
;   asm volatile("s_waitcnt lgkmcnt(0)" ::: "memory"); SBAR();
;     ...
;   od = __builtin_amdgcn_mfma_f32_32x32x16_bf16(pa0, PK(l0, h0), od, 0, 0, 0);
.LBB0_60:
	ds_read_b128 v[64:67], v184 offset:49152
	ds_read_b128 v[68:71], v184 offset:57344
	ds_read_b128 v[210:213], v187 offset:49152
	ds_read_b128 v[214:217], v187 offset:57344
	v_add_f32_e32 v162, 0, v206
	v_add_f32_e32 v162, v208, v162
	s_waitcnt lgkmcnt(3)
	v_mfma_f32_32x32x16_bf16 v[80:95], v[64:67], v[126:129], 0
	v_add_f32_e32 v162, v163, v162
	v_add_f32_e32 v162, v207, v162
	v_add_f32_e32 v162, v164, v162
	v_add_f32_e32 v162, v205, v162
	v_add_f32_e32 v162, v165, v162
	v_add_f32_e32 v162, v204, v162
	v_add_f32_e32 v162, v201, v162
	s_waitcnt lgkmcnt(2)
	v_mfma_f32_32x32x16_bf16 v[64:79], v[68:71], v[126:129], 0
	v_add_f32_e32 v162, v203, v162
	v_add_f32_e32 v162, v200, v162
	v_add_f32_e32 v162, v202, v162
	v_exp_f32_e32 v158, v158
	v_add_f32_e32 v162, v197, v162
	v_exp_f32_e32 v159, v159
	v_add_f32_e32 v162, v199, v162
	s_waitcnt lgkmcnt(1)
	v_mfma_f32_32x32x16_bf16 v[80:95], v[210:213], v[122:125], v[80:95]
	v_exp_f32_e32 v156, v156
	v_add_f32_e32 v162, v196, v162
	v_exp_f32_e32 v157, v157
	v_add_f32_e32 v162, v198, v162
	v_exp_f32_e32 v150, v150
	v_add_f32_e32 v162, v158, v162
	v_exp_f32_e32 v151, v151
	s_waitcnt lgkmcnt(0)
	v_mfma_f32_32x32x16_bf16 v[64:79], v[214:217], v[122:125], v[64:79]
	ds_read_b128 v[210:213], v185 offset:49152
	ds_read_b128 v[214:217], v185 offset:57344
	v_add_f32_e32 v162, v159, v162
	v_exp_f32_e32 v148, v148
	v_add_f32_e32 v162, v156, v162
	v_exp_f32_e32 v149, v149
	v_add_f32_e32 v162, v157, v162
	v_exp_f32_e32 v146, v146
	s_waitcnt lgkmcnt(1)
	v_mfma_f32_32x32x16_bf16 v[80:95], v[210:213], v[118:121], v[80:95]
	v_add_f32_e32 v162, v150, v162
	v_exp_f32_e32 v147, v147
	v_add_f32_e32 v162, v151, v162
	v_exp_f32_e32 v160, v160
	v_add_f32_e32 v162, v148, v162
	v_exp_f32_e32 v161, v161
	v_add_f32_e32 v162, v149, v162
	s_waitcnt lgkmcnt(0)
	v_mfma_f32_32x32x16_bf16 v[64:79], v[214:217], v[118:121], v[64:79]
	ds_read_b128 v[210:213], v186 offset:49152
	ds_read_b128 v[214:217], v186 offset:57344
	v_exp_f32_e32 v154, v154
	v_add_f32_e32 v162, v146, v162
	v_exp_f32_e32 v155, v155
	v_add_f32_e32 v162, v147, v162
	v_exp_f32_e32 v152, v152
	v_add_f32_e32 v162, v160, v162
	s_waitcnt lgkmcnt(1)
	v_mfma_f32_32x32x16_bf16 v[80:95], v[210:213], v[114:117], v[80:95]
	v_exp_f32_e32 v153, v153
	v_add_f32_e32 v162, v161, v162
	v_add_f32_e32 v162, v154, v162
	v_add_f32_e32 v162, v155, v162
	v_add_f32_e32 v162, v152, v162
	v_add_f32_e32 v194, v153, v162
	v_mov_b32_e32 v195, v194
	s_waitcnt lgkmcnt(0)
	v_mfma_f32_32x32x16_bf16 v[64:79], v[214:217], v[114:117], v[64:79]
	ds_read_b128 v[210:213], v188 offset:49152
	ds_read_b128 v[214:217], v188 offset:57344
	v_permlane32_swap_b32_e32 v194, v195
	s_waitcnt lgkmcnt(1)
	v_mfma_f32_32x32x16_bf16 v[80:95], v[210:213], v[110:113], v[80:95]
	s_waitcnt lgkmcnt(0)
	v_mfma_f32_32x32x16_bf16 v[64:79], v[214:217], v[110:113], v[64:79]
	ds_read_b128 v[210:213], v189 offset:49152
	ds_read_b128 v[214:217], v189 offset:57344
	s_waitcnt lgkmcnt(1)
	v_mfma_f32_32x32x16_bf16 v[80:95], v[210:213], v[106:109], v[80:95]
	s_waitcnt lgkmcnt(0)
	v_mfma_f32_32x32x16_bf16 v[64:79], v[214:217], v[106:109], v[64:79]
	ds_read_b128 v[210:213], v190 offset:49152
	ds_read_b128 v[214:217], v190 offset:57344
	s_waitcnt lgkmcnt(1)
	v_mfma_f32_32x32x16_bf16 v[80:95], v[210:213], v[102:105], v[80:95]
	s_waitcnt lgkmcnt(0)
	v_mfma_f32_32x32x16_bf16 v[64:79], v[214:217], v[102:105], v[64:79]
	ds_read_b128 v[210:213], v191 offset:49152
	ds_read_b128 v[214:217], v191 offset:57344
	v_cvt_pk_bf16_f32 v162, v206, v208
	v_cvt_pk_bf16_f32 v163, v163, v207
	v_cvt_pk_bf16_f32 v164, v164, v205
	v_cvt_pk_bf16_f32 v165, v165, v204
	v_cvt_pk_bf16_f32 v204, v201, v203
	v_cvt_pk_bf16_f32 v205, v200, v202
	s_waitcnt lgkmcnt(1)
	v_mfma_f32_32x32x16_bf16 v[80:95], v[210:213], v[98:101], v[80:95]
	v_permlane32_swap_b32_e32 v162, v164
	v_cvt_pk_bf16_f32 v206, v197, v199
	v_cvt_pk_bf16_f32 v207, v196, v198
	v_cvt_pk_bf16_f32 v196, v158, v159
	v_cvt_pk_bf16_f32 v197, v156, v157
	v_cvt_pk_bf16_f32 v198, v150, v151
	s_waitcnt lgkmcnt(0)
	v_mfma_f32_32x32x16_bf16 v[64:79], v[214:217], v[98:101], v[64:79]
	v_cvt_pk_bf16_f32 v199, v148, v149
	v_cvt_pk_bf16_f32 v200, v146, v147
	v_cvt_pk_bf16_f32 v201, v160, v161
	v_cvt_pk_bf16_f32 v202, v154, v155
	v_cvt_pk_bf16_f32 v203, v152, v153
	v_permlane32_swap_b32_e32 v163, v165
	v_permlane32_swap_b32_e32 v204, v206
	v_permlane32_swap_b32_e32 v205, v207
	v_permlane32_swap_b32_e32 v196, v198
	v_permlane32_swap_b32_e32 v197, v199
	v_permlane32_swap_b32_e32 v200, v202
	v_permlane32_swap_b32_e32 v201, v203
	s_mov_b32 s6, 0xfffd0000
	v_add_co_u32_e32 v150, vcc, s6, v170
	s_nop 1
	v_addc_co_u32_e32 v151, vcc, -1, v171, vcc
	global_load_dwordx4 v[146:149], v[150:151], off
	s_nop 0
	global_load_dwordx4 v[150:153], v[150:151], off offset:-1024
	s_nop 0
	global_load_dwordx4 v[158:161], v[170:171], off
	global_load_dwordx4 v[154:157], v[170:171], off offset:-1024
	ds_read_b64_tr_b16 v[208:209], v174 offset:0
	ds_read_b64_tr_b16 v[210:211], v174 offset:0x800
	ds_read_b64_tr_b16 v[212:213], v174 offset:0x1000
	ds_read_b64_tr_b16 v[214:215], v174 offset:0x1800
	ds_read_b64_tr_b16 v[216:217], v174 offset:0x2000
	ds_read_b64_tr_b16 v[218:219], v174 offset:0x2800
	ds_read_b64_tr_b16 v[220:221], v174 offset:0x3000
	ds_read_b64_tr_b16 v[222:223], v174 offset:0x3800
	s_waitcnt lgkmcnt(6)
	s_nop 0
	v_mfma_f32_32x32x16_bf16 v[0:15], v[162:165], v[208:211], v[0:15]
	ds_read_b64_tr_b16 v[208:209], v174 offset:0x200
	ds_read_b64_tr_b16 v[210:211], v174 offset:0xa00
	s_waitcnt lgkmcnt(6)
	v_mfma_f32_32x32x16_bf16 v[0:15], v[204:207], v[212:215], v[0:15]
	ds_read_b64_tr_b16 v[212:213], v174 offset:0x1200
	ds_read_b64_tr_b16 v[214:215], v174 offset:0x1a00
	s_waitcnt lgkmcnt(6)
; __device__ __forceinline__ void partialSM(f32x16& p0, f32x16& p1, float& m_reg, float& mn, float& alpha) {
; template <int OFF> __device__ __forceinline__ s16x4 tr_read(int vb) {
;   s16x4 r; asm volatile("ds_read_b64_tr_b16 %0, %1 offset:%2" : "=&v"(r) : "v"(vb), "i"(OFF) : "memory"); return r;
; }
; template <int D0> __device__ __forceinline__ void pv_one(f32x16& od, int vb, bf16x8 pa0, bf16x8 pa1, bf16x8 pa2, bf16x8 pa3) {
;   const s16x4 l0 = tr_read<v_rd_off(D0, 0, 0)>(vb), h0 = tr_read<v_rd_off(D0, 0, 1)>(vb), l1 = tr_read<v_rd_off(D0, 1, 0)>(vb), h1 = tr_read<v_rd_off(D0, 1, 1)>(vb);
;   const s16x4 l2 = tr_read<v_rd_off(D0, 2, 0)>(vb), h2 = tr_read<v_rd_off(D0, 2, 1)>(vb), l3 = tr_read<v_rd_off(D0, 3, 0)>(vb), h3 = tr_read<v_rd_off(D0, 3, 1)>(vb);
;   asm volatile("s_waitcnt lgkmcnt(0)" ::: "memory"); SBAR();
;     ...
;   od = __builtin_amdgcn_mfma_f32_32x32x16_bf16(pa0, PK(l0, h0), od, 0, 0, 0);
;   od = __builtin_amdgcn_mfma_f32_32x32x16_bf16(pa1, PK(l1, h1), od, 0, 0, 0);
;   od = __builtin_amdgcn_mfma_f32_32x32x16_bf16(pa2, PK(l2, h2), od, 0, 0, 0);
;   od = __builtin_amdgcn_mfma_f32_32x32x16_bf16(pa3, PK(l3, h3), od, 0, 0, 0);
;     ...
; }
; __device__ __forceinline__ void pv_d0(f32x16* o, int vb, bf16x8 pa0, bf16x8 pa1, bf16x8 pa2, bf16x8 pa3) {
;   pv_one<0>(o[0], vb, pa0, pa1, pa2, pa3); pv_one<1>(o[1], vb, pa0, pa1, pa2, pa3); pv_one<2>(o[2], vb, pa0, pa1, pa2, pa3); pv_one<3>(o[3], vb, pa0, pa1, pa2, pa3);
; }
; __device__ __forceinline__ void attn_dense_body(const bf16_t* __restrict__ Qb, const bf16_t* __restrict__ Kh, const bf16_t* __restrict__ Vh,
;                                                 bf16_t* __restrict__ Ob, int seq, char* lds, const Ctx& cx) {
;   const int tid = cx.tid_(), wid = tid >> 6, lane = tid & 63, r32 = lane & 31, hi = lane >> 5;
;   bf16_t* V_lds = (bf16_t*)lds; bf16_t* K_lds = (bf16_t*)(lds + 2 * SHM_V);
;   float* ws = (float*)(lds + 2 * SHM_V + 2 * SHM_K) + wid * 64; float* li_l = ws; float* al_l = ws + 32;
;   float m_reg = -1e30f, l_reg = 0; f32x16 o[4] = {}; bf16x8 qr[8];
;   const bf16_t* Qw = Qb + (long)(wid * QBLK + r32) * LDQ + hi * 8;
; #pragma unroll
;   for (int d0 = 0; d0 < 8; ++d0) qr[d0] = ld8(Qw + d0 * 16);
;   const int sr = tid >> 4, sc = (tid & 15) * 8, vst0 = v_st(sr, sc), vst1 = v_st(32 + sr, sc);
;   const int vb0 = (int)(uintptr_t)V_lds + v_rd_base(lane);
;   struct { bf16x8 vs0, vs1, ks0, ks1; } sr_[2];
	v_mfma_f32_32x32x16_bf16 v[0:15], v[196:199], v[216:219], v[0:15]
	ds_read_b64_tr_b16 v[216:217], v174 offset:0x2200
	ds_read_b64_tr_b16 v[218:219], v174 offset:0x2a00
	s_waitcnt lgkmcnt(6)
	v_mfma_f32_32x32x16_bf16 v[0:15], v[200:203], v[220:223], v[0:15]
	ds_read_b64_tr_b16 v[220:221], v174 offset:0x3200
	ds_read_b64_tr_b16 v[222:223], v174 offset:0x3a00
	s_waitcnt lgkmcnt(6)
	v_mfma_f32_32x32x16_bf16 v[48:63], v[162:165], v[208:211], v[48:63]
	ds_read_b64_tr_b16 v[208:209], v174 offset:0x400
	ds_read_b64_tr_b16 v[210:211], v174 offset:0xc00
	s_waitcnt lgkmcnt(6)
	v_mfma_f32_32x32x16_bf16 v[48:63], v[204:207], v[212:215], v[48:63]
	ds_read_b64_tr_b16 v[212:213], v174 offset:0x1400
	ds_read_b64_tr_b16 v[214:215], v174 offset:0x1c00
	s_waitcnt lgkmcnt(6)
	v_mfma_f32_32x32x16_bf16 v[48:63], v[196:199], v[216:219], v[48:63]
	ds_read_b64_tr_b16 v[216:217], v174 offset:0x2400
	ds_read_b64_tr_b16 v[218:219], v174 offset:0x2c00
	s_waitcnt lgkmcnt(6)
	v_mfma_f32_32x32x16_bf16 v[48:63], v[200:203], v[220:223], v[48:63]
	ds_read_b64_tr_b16 v[220:221], v174 offset:0x3400
	ds_read_b64_tr_b16 v[222:223], v174 offset:0x3c00
	s_waitcnt lgkmcnt(6)
	v_mfma_f32_32x32x16_bf16 v[32:47], v[162:165], v[208:211], v[32:47]
	ds_read_b64_tr_b16 v[208:209], v174 offset:0x600
	ds_read_b64_tr_b16 v[210:211], v174 offset:0xe00
	s_waitcnt lgkmcnt(6)
	v_mfma_f32_32x32x16_bf16 v[32:47], v[204:207], v[212:215], v[32:47]
	ds_read_b64_tr_b16 v[212:213], v174 offset:0x1600
	ds_read_b64_tr_b16 v[214:215], v174 offset:0x1e00
	s_waitcnt lgkmcnt(6)
	v_mfma_f32_32x32x16_bf16 v[32:47], v[196:199], v[216:219], v[32:47]
	ds_read_b64_tr_b16 v[216:217], v174 offset:0x2600
	ds_read_b64_tr_b16 v[218:219], v174 offset:0x2e00
	s_waitcnt lgkmcnt(6)
	v_mfma_f32_32x32x16_bf16 v[32:47], v[200:203], v[220:223], v[32:47]
	ds_read_b64_tr_b16 v[220:221], v174 offset:0x3600
	ds_read_b64_tr_b16 v[222:223], v174 offset:0x3e00
	s_waitcnt lgkmcnt(6)
	v_mfma_f32_32x32x16_bf16 v[16:31], v[162:165], v[208:211], v[16:31]
	v_max_f32_e32 v162, v81, v81
	v_max_f32_e32 v163, v80, v80
	v_max_f32_e32 v162, v163, v162
	v_max3_f32 v162, v162, v82, v83
	v_max3_f32 v162, v162, v84, v85
	v_max3_f32 v162, v162, v86, v87
	v_max3_f32 v162, v162, v88, v89
	v_max3_f32 v162, v162, v90, v91
	v_max3_f32 v162, v162, v92, v93
	s_waitcnt lgkmcnt(4)
	v_mfma_f32_32x32x16_bf16 v[16:31], v[204:207], v[212:215], v[16:31]
	v_max3_f32 v162, v162, v94, v95
	v_max3_f32 v162, v162, v64, v65
	v_max3_f32 v162, v162, v66, v67
	v_max3_f32 v162, v162, v68, v69
	v_max3_f32 v162, v162, v70, v71
	v_max3_f32 v162, v162, v72, v73
	v_max3_f32 v162, v162, v74, v75
	v_max3_f32 v162, v162, v76, v77
	s_waitcnt lgkmcnt(2)
	v_mfma_f32_32x32x16_bf16 v[16:31], v[196:199], v[216:219], v[16:31]
	v_max3_f32 v162, v162, v78, v79
	v_mov_b32_e32 v163, v162
	s_nop 1
	v_permlane32_swap_b32_e32 v162, v163
	v_max_f32_e32 v163, v163, v163
	v_max_f32_e32 v162, v162, v162
	v_max_f32_e32 v162, v162, v163
	v_sub_f32_e32 v163, v162, v193
	v_cmp_ge_f32_e32 vcc, s29, v163
	v_max_f32_e32 v163, v193, v193
	v_max_f32_e32 v162, v163, v162
	s_waitcnt lgkmcnt(0)
	v_mfma_f32_32x32x16_bf16 v[16:31], v[200:203], v[220:223], v[16:31]
	v_sub_f32_e32 v163, v193, v162
	v_mul_f32_e32 v163, 0x3e0293ee, v163
	v_exp_f32_e32 v163, v163
	s_cmp_eq_u64 vcc, exec
	s_cselect_b64 s[6:7], -1, 0
	s_barrier
	s_waitcnt vmcnt(4)
	v_cndmask_b32_e64 v209, v163, 1.0, s[6:7]
	v_cmp_gt_f32_e32 vcc, 1.0, v209
	s_waitcnt vmcnt(7)
	ds_write_b128 v177, v[130:133]
	s_waitcnt vmcnt(5)
	ds_write_b128 v178, v[134:137]
	s_waitcnt vmcnt(5)
	ds_write_b128 v180, v[138:141] offset:32768
	s_waitcnt vmcnt(4)
	ds_write_b128 v183, v[142:145] offset:32768
	s_cbranch_vccz .LBB0_64
	s_and_saveexec_b64 s[14:15], s[4:5]
	ds_write_b32 v179, v209 offset:128
	s_or_b64 exec, exec, s[14:15]
	s_waitcnt lgkmcnt(0)
	v_add_u32_e32 v142, v167, v96
	ds_read_b128 v[130:133], v142 offset:224
	ds_read_b128 v[134:137], v142 offset:192
	ds_read_b128 v[138:141], v142 offset:160
	ds_read_b128 v[142:145], v142 offset:128
	s_waitcnt lgkmcnt(3)
	v_pk_mul_f32 v[12:13], v[12:13], v[130:131]
	s_waitcnt lgkmcnt(2)
	v_pk_mul_f32 v[8:9], v[8:9], v[134:135]
	s_waitcnt lgkmcnt(1)
	v_pk_mul_f32 v[4:5], v[4:5], v[138:139]
	v_pk_mul_f32 v[14:15], v[14:15], v[132:133]
	v_pk_mul_f32 v[10:11], v[10:11], v[136:137]
	v_pk_mul_f32 v[6:7], v[6:7], v[140:141]
	s_waitcnt lgkmcnt(0)
	v_pk_mul_f32 v[2:3], v[2:3], v[144:145]
	v_pk_mul_f32 v[0:1], v[0:1], v[142:143]
	v_pk_mul_f32 v[60:61], v[60:61], v[130:131]
	v_pk_mul_f32 v[56:57], v[56:57], v[134:135]
	v_pk_mul_f32 v[52:53], v[52:53], v[138:139]
	v_pk_mul_f32 v[62:63], v[62:63], v[132:133]
	v_pk_mul_f32 v[58:59], v[58:59], v[136:137]
	v_pk_mul_f32 v[54:55], v[54:55], v[140:141]
	v_pk_mul_f32 v[50:51], v[50:51], v[144:145]
	v_pk_mul_f32 v[48:49], v[48:49], v[142:143]
	v_pk_mul_f32 v[44:45], v[44:45], v[130:131]
	v_pk_mul_f32 v[40:41], v[40:41], v[134:135]
	v_pk_mul_f32 v[36:37], v[36:37], v[138:139]
	v_pk_mul_f32 v[46:47], v[46:47], v[132:133]
	v_pk_mul_f32 v[42:43], v[42:43], v[136:137]
	v_pk_mul_f32 v[38:39], v[38:39], v[140:141]
	v_pk_mul_f32 v[34:35], v[34:35], v[144:145]
	v_pk_mul_f32 v[32:33], v[32:33], v[142:143]
	v_pk_mul_f32 v[28:29], v[28:29], v[130:131]
	v_pk_mul_f32 v[24:25], v[24:25], v[134:135]
	v_pk_mul_f32 v[20:21], v[20:21], v[138:139]
	v_pk_mul_f32 v[30:31], v[30:31], v[132:133]
	v_pk_mul_f32 v[26:27], v[26:27], v[136:137]
	v_pk_mul_f32 v[22:23], v[22:23], v[140:141]
	v_pk_mul_f32 v[18:19], v[18:19], v[144:145]
	v_pk_mul_f32 v[16:17], v[16:17], v[142:143]
; __device__ __forceinline__ void partialSM(f32x16& p0, f32x16& p1, float& m_reg, float& mn, float& alpha) {
;   constexpr float C = SCALE * 1.4426950408889634f;
;   float pmax = p0[0];
; #pragma unroll
;   for (int r = 1; r < 16; ++r) pmax = fmaxf(pmax, p0[r]);
; #pragma unroll
;   for (int r = 0; r < 16; ++r) pmax = fmaxf(pmax, p1[r]);
;   { auto rr = __builtin_amdgcn_permlane32_swap(__float_as_uint(pmax), __float_as_uint(pmax), false, false);
;     pmax = fmaxf(__uint_as_float(rr[0]), __uint_as_float(rr[1])); }
;   if (__builtin_expect(__all(pmax - m_reg <= THR / SCALE), 1)) { mn = m_reg; alpha = 1.f; }
;   else { mn = fmaxf(m_reg, pmax); alpha = __builtin_amdgcn_exp2f((m_reg - mn) * C); m_reg = mn; }
;   float mnC = -mn * C;
; #pragma unroll
;   for (int r = 0; r < 16; ++r) p0[r] = fmaf(p0[r], C, mnC);
; #pragma unroll
;   for (int r = 0; r < 16; ++r) p1[r] = fmaf(p1[r], C, mnC);
; #pragma unroll
;   for (int r = 0; r < 16; ++r) p0[r] = __builtin_amdgcn_exp2f(p0[r]);
; }
; __device__ __forceinline__ void finishSM(f32x16& p0, f32x16& p1, float alpha, float& l_reg, bf16x8& pa0, bf16x8& pa1, bf16x8& pa2, bf16x8& pa3) {
; #pragma unroll
;   for (int r = 0; r < 16; ++r) p1[r] = __builtin_amdgcn_exp2f(p1[r]);
;   float ps = 0;
; #pragma unroll
;   for (int r = 0; r < 16; ++r) ps += p0[r];
; #pragma unroll
;   for (int r = 0; r < 16; ++r) ps += p1[r];
;   { auto rr = __builtin_amdgcn_permlane32_swap(__float_as_uint(ps), __float_as_uint(ps), false, false);
;     ps = __uint_as_float(rr[0]) + __uint_as_float(rr[1]); }
;   l_reg = l_reg * alpha + ps;
;     ...
;   PK4(p0, 0, pa0); PK4(p0, 8, pa1); PK4(p1, 0, pa2); PK4(p1, 8, pa3);
;     ...
; }
; __device__ __forceinline__ void qkt(f32x16& p0, f32x16& p1, const bf16_t* Ks, const bf16x8* qr, int r32, int hi) {
;   p0 = f32x16{}; p1 = f32x16{};
; #pragma unroll
;   for (int d0 = 0; d0 < 8; ++d0) { int cb = (d0 * 16 + hi * 8) * 2;
;     bf16x8 b0 = *reinterpret_cast<const bf16x8*>((const char*)Ks + KSWZ(r32, cb));
;     bf16x8 b1 = *reinterpret_cast<const bf16x8*>((const char*)Ks + KSWZ(32 + r32, cb));
;     p0 = __builtin_amdgcn_mfma_f32_32x32x16_bf16(b0, qr[d0], p0, 0, 0, 0);
;     p1 = __builtin_amdgcn_mfma_f32_32x32x16_bf16(b1, qr[d0], p1, 0, 0, 0); }
; }
.LBB0_64:
	v_cndmask_b32_e64 v193, v162, v193, s[6:7]
	v_mul_f32_e32 v162, 0xbe0293ee, v193
	v_fmamk_f32 v80, v80, 0x3e0293ee, v162
	v_fmamk_f32 v81, v81, 0x3e0293ee, v162
	v_fmamk_f32 v82, v82, 0x3e0293ee, v162
	v_fmamk_f32 v83, v83, 0x3e0293ee, v162
	v_fmamk_f32 v84, v84, 0x3e0293ee, v162
	v_fmamk_f32 v85, v85, 0x3e0293ee, v162
	v_fmamk_f32 v86, v86, 0x3e0293ee, v162
	v_fmamk_f32 v87, v87, 0x3e0293ee, v162
	v_fmamk_f32 v88, v88, 0x3e0293ee, v162
	v_fmamk_f32 v89, v89, 0x3e0293ee, v162
	v_fmamk_f32 v90, v90, 0x3e0293ee, v162
	v_fmamk_f32 v91, v91, 0x3e0293ee, v162
	v_fmamk_f32 v92, v92, 0x3e0293ee, v162
	v_fmamk_f32 v93, v93, 0x3e0293ee, v162
	v_fmamk_f32 v94, v94, 0x3e0293ee, v162
	v_fmamk_f32 v95, v95, 0x3e0293ee, v162
	v_exp_f32_e32 v143, v80
	v_exp_f32_e32 v145, v81
	v_exp_f32_e32 v141, v82
	v_exp_f32_e32 v144, v83
	v_exp_f32_e32 v140, v84
	v_exp_f32_e32 v142, v85
	v_exp_f32_e32 v138, v86
	v_exp_f32_e32 v139, v87
	v_exp_f32_e32 v135, v88
	v_exp_f32_e32 v137, v89
	v_exp_f32_e32 v134, v90
	v_exp_f32_e32 v136, v91
	v_exp_f32_e32 v131, v92
	v_exp_f32_e32 v133, v93
	v_exp_f32_e32 v130, v94
	v_exp_f32_e32 v132, v95
	v_fmamk_f32 v201, v64, 0x3e0293ee, v162
	v_fmamk_f32 v202, v65, 0x3e0293ee, v162
	v_fmamk_f32 v203, v66, 0x3e0293ee, v162
	v_fmamk_f32 v204, v67, 0x3e0293ee, v162
	v_fmamk_f32 v205, v68, 0x3e0293ee, v162
	v_fmamk_f32 v164, v69, 0x3e0293ee, v162
	v_fmamk_f32 v165, v70, 0x3e0293ee, v162
	v_fmamk_f32 v196, v71, 0x3e0293ee, v162
	v_fmamk_f32 v197, v72, 0x3e0293ee, v162
	v_fmamk_f32 v198, v73, 0x3e0293ee, v162
	v_fmamk_f32 v199, v74, 0x3e0293ee, v162
	v_fmamk_f32 v200, v75, 0x3e0293ee, v162
	v_fmamk_f32 v163, v76, 0x3e0293ee, v162
	v_fmamk_f32 v206, v77, 0x3e0293ee, v162
	v_fmamk_f32 v207, v78, 0x3e0293ee, v162
	v_fmac_f32_e32 v162, 0x3e0293ee, v79
	s_add_i32 s23, s23, 2
	s_waitcnt lgkmcnt(0)
	s_barrier
	ds_read_b128 v[64:67], v184 offset:32768
	ds_read_b128 v[68:71], v184 offset:40960
	ds_read_b128 v[210:213], v187 offset:32768
	ds_read_b128 v[214:217], v187 offset:40960
	v_exp_f32_e32 v219, v162
	v_add_f32_e32 v162, 0, v143
	s_waitcnt lgkmcnt(3)
	v_mfma_f32_32x32x16_bf16 v[80:95], v[64:67], v[126:129], 0
	v_add_f32_e32 v162, v145, v162
	v_add_f32_e32 v162, v141, v162
	v_add_f32_e32 v162, v144, v162
	v_add_f32_e32 v162, v140, v162
	v_add_f32_e32 v162, v142, v162
	v_add_f32_e32 v162, v138, v162
	v_add_f32_e32 v162, v139, v162
	s_waitcnt lgkmcnt(2)
	v_mfma_f32_32x32x16_bf16 v[64:79], v[68:71], v[126:129], 0
	v_add_f32_e32 v162, v135, v162
	v_add_f32_e32 v162, v137, v162
	v_add_f32_e32 v162, v134, v162
	v_add_f32_e32 v162, v136, v162
	v_exp_f32_e32 v201, v201
	v_add_f32_e32 v162, v131, v162
	v_exp_f32_e32 v202, v202
	s_waitcnt lgkmcnt(1)
	v_mfma_f32_32x32x16_bf16 v[80:95], v[210:213], v[122:125], v[80:95]
	v_add_f32_e32 v162, v133, v162
	v_exp_f32_e32 v203, v203
	v_add_f32_e32 v162, v130, v162
	v_exp_f32_e32 v204, v204
	v_add_f32_e32 v162, v132, v162
	v_exp_f32_e32 v205, v205
	v_add_f32_e32 v162, v201, v162
	s_waitcnt lgkmcnt(0)
	v_mfma_f32_32x32x16_bf16 v[64:79], v[214:217], v[122:125], v[64:79]
	ds_read_b128 v[210:213], v185 offset:32768
	ds_read_b128 v[214:217], v185 offset:40960
	v_exp_f32_e32 v208, v164
	v_add_f32_e32 v162, v202, v162
	v_add_f32_e32 v162, v203, v162
	v_add_f32_e32 v162, v204, v162
	v_add_f32_e32 v162, v205, v162
	v_add_f32_e32 v162, v208, v162
	s_waitcnt lgkmcnt(1)
	v_mfma_f32_32x32x16_bf16 v[80:95], v[210:213], v[118:121], v[80:95]
	v_exp_f32_e32 v218, v163
	v_exp_f32_e32 v206, v206
	v_exp_f32_e32 v207, v207
	s_waitcnt lgkmcnt(0)
	v_mfma_f32_32x32x16_bf16 v[64:79], v[214:217], v[118:121], v[64:79]
	ds_read_b128 v[210:213], v186 offset:32768
	ds_read_b128 v[214:217], v186 offset:40960
	s_waitcnt lgkmcnt(1)
	v_mfma_f32_32x32x16_bf16 v[80:95], v[210:213], v[114:117], v[80:95]
	s_waitcnt lgkmcnt(0)
	v_mfma_f32_32x32x16_bf16 v[64:79], v[214:217], v[114:117], v[64:79]
	ds_read_b128 v[210:213], v188 offset:32768
	ds_read_b128 v[214:217], v188 offset:40960
	s_waitcnt lgkmcnt(1)
	v_mfma_f32_32x32x16_bf16 v[80:95], v[210:213], v[110:113], v[80:95]
	s_waitcnt lgkmcnt(0)
	v_mfma_f32_32x32x16_bf16 v[64:79], v[214:217], v[110:113], v[64:79]
	ds_read_b128 v[210:213], v189 offset:32768
	ds_read_b128 v[214:217], v189 offset:40960
	s_waitcnt lgkmcnt(1)
	v_mfma_f32_32x32x16_bf16 v[80:95], v[210:213], v[106:109], v[80:95]
	s_waitcnt lgkmcnt(0)
	v_mfma_f32_32x32x16_bf16 v[64:79], v[214:217], v[106:109], v[64:79]
	ds_read_b128 v[210:213], v190 offset:32768
	ds_read_b128 v[214:217], v190 offset:40960
	s_waitcnt lgkmcnt(1)
	v_mfma_f32_32x32x16_bf16 v[80:95], v[210:213], v[102:105], v[80:95]
	s_waitcnt lgkmcnt(0)
	v_mfma_f32_32x32x16_bf16 v[64:79], v[214:217], v[102:105], v[64:79]
	ds_read_b128 v[210:213], v191 offset:32768
	ds_read_b128 v[214:217], v191 offset:40960
	s_waitcnt lgkmcnt(1)
	v_mfma_f32_32x32x16_bf16 v[80:95], v[210:213], v[98:101], v[80:95]
	v_exp_f32_e32 v212, v165
	v_exp_f32_e32 v213, v196
	v_add_f32_e32 v162, v212, v162
	v_add_f32_e32 v162, v213, v162
	s_waitcnt lgkmcnt(0)
; __device__ __forceinline__ void finishSM(f32x16& p0, f32x16& p1, float alpha, float& l_reg, bf16x8& pa0, bf16x8& pa1, bf16x8& pa2, bf16x8& pa3) {
; #pragma unroll
;   for (int r = 0; r < 16; ++r) p1[r] = __builtin_amdgcn_exp2f(p1[r]);
;   float ps = 0;
; #pragma unroll
;   for (int r = 0; r < 16; ++r) ps += p0[r];
; #pragma unroll
;   for (int r = 0; r < 16; ++r) ps += p1[r];
;   { auto rr = __builtin_amdgcn_permlane32_swap(__float_as_uint(ps), __float_as_uint(ps), false, false);
;     ps = __uint_as_float(rr[0]) + __uint_as_float(rr[1]); }
;   l_reg = l_reg * alpha + ps;
;     ...
;   PK4(p0, 0, pa0); PK4(p0, 8, pa1); PK4(p1, 0, pa2); PK4(p1, 8, pa3);
;     ...
; }
; __device__ __forceinline__ void qkt(f32x16& p0, f32x16& p1, const bf16_t* Ks, const bf16x8* qr, int r32, int hi) {
;   p0 = f32x16{}; p1 = f32x16{};
; #pragma unroll
;   for (int d0 = 0; d0 < 8; ++d0) { int cb = (d0 * 16 + hi * 8) * 2;
;     bf16x8 b0 = *reinterpret_cast<const bf16x8*>((const char*)Ks + KSWZ(r32, cb));
;     bf16x8 b1 = *reinterpret_cast<const bf16x8*>((const char*)Ks + KSWZ(32 + r32, cb));
;     p0 = __builtin_amdgcn_mfma_f32_32x32x16_bf16(b0, qr[d0], p0, 0, 0, 0);
;     p1 = __builtin_amdgcn_mfma_f32_32x32x16_bf16(b1, qr[d0], p1, 0, 0, 0); }
; }
; __device__ __forceinline__ int v_st(int k, int c) { const int kk = (k & ~0xC) | ((k & 4) << 1) | ((k & 8) >> 1); return ((kk >> 3) * 4 + (c >> 5)) * 512 + ((kk & 7) * 32 + (c & 31)) * 2; }
; __device__ __forceinline__ int v_rd_base(int lane) { return ((lane & 3) << 3) | (((lane >> 2) & 3) << 6) | (((lane >> 4) & 1) << 5) | (((lane >> 5) & 1) << 8); }
; template <int OFF> __device__ __forceinline__ s16x4 tr_read(int vb) {
;   s16x4 r; asm volatile("ds_read_b64_tr_b16 %0, %1 offset:%2" : "=&v"(r) : "v"(vb), "i"(OFF) : "memory"); return r;
; }
; template <int D0> __device__ __forceinline__ void pv_one(f32x16& od, int vb, bf16x8 pa0, bf16x8 pa1, bf16x8 pa2, bf16x8 pa3) {
;   const s16x4 l0 = tr_read<v_rd_off(D0, 0, 0)>(vb), h0 = tr_read<v_rd_off(D0, 0, 1)>(vb), l1 = tr_read<v_rd_off(D0, 1, 0)>(vb), h1 = tr_read<v_rd_off(D0, 1, 1)>(vb);
;   const s16x4 l2 = tr_read<v_rd_off(D0, 2, 0)>(vb), h2 = tr_read<v_rd_off(D0, 2, 1)>(vb), l3 = tr_read<v_rd_off(D0, 3, 0)>(vb), h3 = tr_read<v_rd_off(D0, 3, 1)>(vb);
;   asm volatile("s_waitcnt lgkmcnt(0)" ::: "memory"); SBAR();
;     ...
;   od = __builtin_amdgcn_mfma_f32_32x32x16_bf16(pa0, PK(l0, h0), od, 0, 0, 0);
	v_mfma_f32_32x32x16_bf16 v[64:79], v[214:217], v[98:101], v[64:79]
	v_exp_f32_e32 v214, v197
	v_exp_f32_e32 v215, v198
	v_exp_f32_e32 v216, v199
	v_exp_f32_e32 v217, v200
	v_add_f32_e32 v162, v214, v162
	v_add_f32_e32 v162, v215, v162
	v_add_f32_e32 v162, v216, v162
	v_add_f32_e32 v162, v217, v162
	v_add_f32_e32 v162, v218, v162
	v_add_f32_e32 v162, v206, v162
	v_add_f32_e32 v162, v207, v162
	v_add_f32_e32 v210, v219, v162
	v_mov_b32_e32 v211, v210
	v_cvt_pk_bf16_f32 v162, v143, v145
	v_cvt_pk_bf16_f32 v163, v141, v144
	v_cvt_pk_bf16_f32 v164, v140, v142
	v_cvt_pk_bf16_f32 v165, v138, v139
	s_nop 1
	v_permlane32_swap_b32_e32 v210, v211
	v_permlane32_swap_b32_e32 v162, v164
	v_permlane32_swap_b32_e32 v163, v165
	v_cvt_pk_bf16_f32 v196, v135, v137
	v_cvt_pk_bf16_f32 v197, v134, v136
	v_cvt_pk_bf16_f32 v198, v131, v133
	v_cvt_pk_bf16_f32 v199, v130, v132
	v_cvt_pk_bf16_f32 v200, v201, v202
	v_cvt_pk_bf16_f32 v201, v203, v204
	v_cvt_pk_bf16_f32 v202, v205, v208
	v_cvt_pk_bf16_f32 v203, v212, v213
	v_cvt_pk_bf16_f32 v204, v214, v215
	v_cvt_pk_bf16_f32 v205, v216, v217
	v_cvt_pk_bf16_f32 v206, v218, v206
	v_cvt_pk_bf16_f32 v207, v207, v219
	s_nop 0
	v_permlane32_swap_b32_e32 v196, v198
	v_permlane32_swap_b32_e32 v197, v199
	v_permlane32_swap_b32_e32 v200, v202
	v_permlane32_swap_b32_e32 v201, v203
	v_permlane32_swap_b32_e32 v204, v206
	v_permlane32_swap_b32_e32 v205, v207
	s_min_u32 s6, s23, 60
	s_lshl_b32 s6, s6, 6
	s_add_i32 s14, s6, 0xc0
	v_add_u32_e32 v130, s14, v175
	v_mad_i64_i32 v[134:135], s[6:7], v130, s35, v[168:169]
	v_add_u32_e32 v130, s14, v176
	v_mad_i64_i32 v[142:143], s[6:7], v130, s35, v[168:169]
	global_load_dwordx4 v[130:133], v[134:135], off offset:1024
	global_load_dwordx4 v[138:141], v[134:135], off
	s_nop 0
	global_load_dwordx4 v[134:137], v[142:143], off offset:1024
	s_nop 0
	global_load_dwordx4 v[142:145], v[142:143], off
	ds_read_b64_tr_b16 v[212:213], v182 offset:0
	ds_read_b64_tr_b16 v[214:215], v182 offset:0x800
	ds_read_b64_tr_b16 v[216:217], v182 offset:0x1000
	ds_read_b64_tr_b16 v[218:219], v182 offset:0x1800
	ds_read_b64_tr_b16 v[220:221], v182 offset:0x2000
	ds_read_b64_tr_b16 v[222:223], v182 offset:0x2800
	ds_read_b64_tr_b16 v[224:225], v182 offset:0x3000
	ds_read_b64_tr_b16 v[226:227], v182 offset:0x3800
	s_waitcnt lgkmcnt(6)
	s_nop 0
	v_mfma_f32_32x32x16_bf16 v[0:15], v[162:165], v[212:215], v[0:15]
	ds_read_b64_tr_b16 v[212:213], v182 offset:0x200
	ds_read_b64_tr_b16 v[214:215], v182 offset:0xa00
	s_waitcnt lgkmcnt(6)
	v_mfma_f32_32x32x16_bf16 v[0:15], v[196:199], v[216:219], v[0:15]
	ds_read_b64_tr_b16 v[216:217], v182 offset:0x1200
	ds_read_b64_tr_b16 v[218:219], v182 offset:0x1a00
	s_waitcnt lgkmcnt(6)
	v_mfma_f32_32x32x16_bf16 v[0:15], v[200:203], v[220:223], v[0:15]
	ds_read_b64_tr_b16 v[220:221], v182 offset:0x2200
	ds_read_b64_tr_b16 v[222:223], v182 offset:0x2a00
	s_waitcnt lgkmcnt(6)
	v_mfma_f32_32x32x16_bf16 v[0:15], v[204:207], v[224:227], v[0:15]
	ds_read_b64_tr_b16 v[224:225], v182 offset:0x3200
	ds_read_b64_tr_b16 v[226:227], v182 offset:0x3a00
	s_waitcnt lgkmcnt(6)
	v_mfma_f32_32x32x16_bf16 v[48:63], v[162:165], v[212:215], v[48:63]
	ds_read_b64_tr_b16 v[212:213], v182 offset:0x400
	ds_read_b64_tr_b16 v[214:215], v182 offset:0xc00
	s_waitcnt lgkmcnt(6)
	v_mfma_f32_32x32x16_bf16 v[48:63], v[196:199], v[216:219], v[48:63]
	ds_read_b64_tr_b16 v[216:217], v182 offset:0x1400
	ds_read_b64_tr_b16 v[218:219], v182 offset:0x1c00
	s_waitcnt lgkmcnt(6)
	v_mfma_f32_32x32x16_bf16 v[48:63], v[200:203], v[220:223], v[48:63]
	ds_read_b64_tr_b16 v[220:221], v182 offset:0x2400
	ds_read_b64_tr_b16 v[222:223], v182 offset:0x2c00
	s_waitcnt lgkmcnt(6)
	v_mfma_f32_32x32x16_bf16 v[48:63], v[204:207], v[224:227], v[48:63]
	ds_read_b64_tr_b16 v[224:225], v182 offset:0x3400
	ds_read_b64_tr_b16 v[226:227], v182 offset:0x3c00
	s_waitcnt lgkmcnt(6)
	v_mfma_f32_32x32x16_bf16 v[32:47], v[162:165], v[212:215], v[32:47]
	ds_read_b64_tr_b16 v[212:213], v182 offset:0x600
	ds_read_b64_tr_b16 v[214:215], v182 offset:0xe00
	s_waitcnt lgkmcnt(6)
	v_mfma_f32_32x32x16_bf16 v[32:47], v[196:199], v[216:219], v[32:47]
	ds_read_b64_tr_b16 v[216:217], v182 offset:0x1600
	ds_read_b64_tr_b16 v[218:219], v182 offset:0x1e00
	s_waitcnt lgkmcnt(6)
	v_mfma_f32_32x32x16_bf16 v[32:47], v[200:203], v[220:223], v[32:47]
	ds_read_b64_tr_b16 v[220:221], v182 offset:0x2600
	ds_read_b64_tr_b16 v[222:223], v182 offset:0x2e00
	s_waitcnt lgkmcnt(6)
	v_mfma_f32_32x32x16_bf16 v[32:47], v[204:207], v[224:227], v[32:47]
	ds_read_b64_tr_b16 v[224:225], v182 offset:0x3600
	ds_read_b64_tr_b16 v[226:227], v182 offset:0x3e00
	s_waitcnt lgkmcnt(6)
	v_mfma_f32_32x32x16_bf16 v[16:31], v[162:165], v[212:215], v[16:31]
	v_max_f32_e32 v162, v81, v81
	v_max_f32_e32 v163, v80, v80
	v_max_f32_e32 v162, v163, v162
	v_max3_f32 v162, v162, v82, v83
	v_max3_f32 v162, v162, v84, v85
	v_max3_f32 v162, v162, v86, v87
	v_max3_f32 v162, v162, v88, v89
	v_max3_f32 v162, v162, v90, v91
	v_max3_f32 v162, v162, v92, v93
	s_waitcnt lgkmcnt(4)
	v_mfma_f32_32x32x16_bf16 v[16:31], v[196:199], v[216:219], v[16:31]
	v_max3_f32 v162, v162, v94, v95
	v_max3_f32 v162, v162, v64, v65
	v_max3_f32 v162, v162, v66, v67
	v_max3_f32 v162, v162, v68, v69
	v_max3_f32 v162, v162, v70, v71
	v_max3_f32 v162, v162, v72, v73
	v_max3_f32 v162, v162, v74, v75
	v_max3_f32 v162, v162, v76, v77
	s_waitcnt lgkmcnt(2)
	v_mfma_f32_32x32x16_bf16 v[16:31], v[200:203], v[220:223], v[16:31]
	v_max3_f32 v162, v162, v78, v79
	v_mov_b32_e32 v163, v162
	s_nop 1
	v_permlane32_swap_b32_e32 v162, v163
	v_max_f32_e32 v163, v163, v163
	v_max_f32_e32 v162, v162, v162
	v_max_f32_e32 v162, v162, v163
	v_sub_f32_e32 v163, v162, v193
	v_cmp_ge_f32_e32 vcc, s29, v163
	v_max_f32_e32 v163, v193, v193
	v_max_f32_e32 v163, v163, v162
	s_waitcnt lgkmcnt(0)
	v_mfma_f32_32x32x16_bf16 v[16:31], v[204:207], v[224:227], v[16:31]
	v_sub_f32_e32 v162, v193, v163
	v_mul_f32_e32 v162, 0x3e0293ee, v162
	v_exp_f32_e32 v162, v162
	s_cmp_eq_u64 vcc, exec
	s_cselect_b64 s[6:7], -1, 0
	s_barrier
; #define SWRITE(b, i) do { *(bf16x8*)((char*)V_lds + (b) * SHM_V + vst0) = sr_[i].vs0;          \
;     *(bf16x8*)((char*)V_lds + (b) * SHM_V + vst1) = sr_[i].vs1; int kc = sc * 2;               \
;     *(bf16x8*)((char*)K_lds + (b) * SHM_K + KSWZ(sr, kc)) = sr_[i].ks0;                       \
;     *(bf16x8*)((char*)K_lds + (b) * SHM_K + KSWZ(32 + sr, kc)) = sr_[i].ks1; } while (0)
; #define SWAIT() asm volatile("s_waitcnt vmcnt(4)" ::: "memory")
; #define RESC(a) do { if (__any((a) < 1.f)) { if (hi == 0) al_l[r32] = (a); asm volatile("s_waitcnt lgkmcnt(0)" ::: "memory"); \
;     _Pragma("unroll") for (int d = 0; d < 4; ++d) _Pragma("unroll") for (int r = 0; r < 16; ++r) o[d][r] *= al_l[crow(r, hi)]; } } while (0)
; __device__ __forceinline__ void attn_dense_body(const bf16_t* __restrict__ Qb, const bf16_t* __restrict__ Kh, const bf16_t* __restrict__ Vh,
;                                                 bf16_t* __restrict__ Ob, int seq, char* lds, const Ctx& cx) {
;     ...
;     __syncthreads(); SWAIT(); SWRITE(1, SO);
;     RESC(alA); __syncthreads();
	s_waitcnt vmcnt(4)
	v_cndmask_b32_e64 v162, v162, 1.0, s[6:7]
	v_cmp_gt_f32_e32 vcc, 1.0, v162
	s_waitcnt vmcnt(7)
	ds_write_b128 v177, v[146:149] offset:16384
	s_waitcnt vmcnt(5)
	ds_write_b128 v178, v[158:161] offset:16384
	ds_write_b128 v180, v[150:153] offset:49152
	s_waitcnt vmcnt(4)
	ds_write_b128 v183, v[154:157] offset:49152
	s_cbranch_vccz .LBB0_68
	s_and_saveexec_b64 s[14:15], s[4:5]
	ds_write_b32 v179, v162 offset:128
	s_or_b64 exec, exec, s[14:15]
	s_waitcnt lgkmcnt(0)
	v_add_u32_e32 v158, v167, v96
	ds_read_b128 v[146:149], v158 offset:224
	ds_read_b128 v[150:153], v158 offset:192
	ds_read_b128 v[154:157], v158 offset:160
	ds_read_b128 v[158:161], v158 offset:128
	s_waitcnt lgkmcnt(3)
	v_pk_mul_f32 v[12:13], v[12:13], v[146:147]
	s_waitcnt lgkmcnt(2)
	v_pk_mul_f32 v[8:9], v[8:9], v[150:151]
	s_waitcnt lgkmcnt(1)
	v_pk_mul_f32 v[4:5], v[4:5], v[154:155]
	v_pk_mul_f32 v[14:15], v[14:15], v[148:149]
	v_pk_mul_f32 v[10:11], v[10:11], v[152:153]
	v_pk_mul_f32 v[6:7], v[6:7], v[156:157]
	s_waitcnt lgkmcnt(0)
	v_pk_mul_f32 v[2:3], v[2:3], v[160:161]
	v_pk_mul_f32 v[0:1], v[0:1], v[158:159]
	v_pk_mul_f32 v[60:61], v[60:61], v[146:147]
	v_pk_mul_f32 v[56:57], v[56:57], v[150:151]
	v_pk_mul_f32 v[52:53], v[52:53], v[154:155]
	v_pk_mul_f32 v[62:63], v[62:63], v[148:149]
	v_pk_mul_f32 v[58:59], v[58:59], v[152:153]
	v_pk_mul_f32 v[54:55], v[54:55], v[156:157]
	v_pk_mul_f32 v[50:51], v[50:51], v[160:161]
	v_pk_mul_f32 v[48:49], v[48:49], v[158:159]
	v_pk_mul_f32 v[44:45], v[44:45], v[146:147]
	v_pk_mul_f32 v[40:41], v[40:41], v[150:151]
	v_pk_mul_f32 v[36:37], v[36:37], v[154:155]
	v_pk_mul_f32 v[46:47], v[46:47], v[148:149]
	v_pk_mul_f32 v[42:43], v[42:43], v[152:153]
	v_pk_mul_f32 v[38:39], v[38:39], v[156:157]
	v_pk_mul_f32 v[34:35], v[34:35], v[160:161]
	v_pk_mul_f32 v[32:33], v[32:33], v[158:159]
	v_pk_mul_f32 v[28:29], v[28:29], v[146:147]
	v_pk_mul_f32 v[24:25], v[24:25], v[150:151]
	v_pk_mul_f32 v[20:21], v[20:21], v[154:155]
	v_pk_mul_f32 v[30:31], v[30:31], v[148:149]
	v_pk_mul_f32 v[26:27], v[26:27], v[152:153]
	v_pk_mul_f32 v[22:23], v[22:23], v[156:157]
	v_pk_mul_f32 v[18:19], v[18:19], v[160:161]
	v_pk_mul_f32 v[16:17], v[16:17], v[158:159]

; __device__ __forceinline__ void finishSM(f32x16& p0, f32x16& p1, float alpha, float& l_reg, bf16x8& pa0, bf16x8& pa1, bf16x8& pa2, bf16x8& pa3) {
; #pragma unroll
;   for (int r = 0; r < 16; ++r) p1[r] = __builtin_amdgcn_exp2f(p1[r]);
;   float ps = 0;
; #pragma unroll
;   for (int r = 0; r < 16; ++r) ps += p0[r];
; #pragma unroll
;   for (int r = 0; r < 16; ++r) ps += p1[r];
;   { auto rr = __builtin_amdgcn_permlane32_swap(__float_as_uint(ps), __float_as_uint(ps), false, false);
;     ps = __uint_as_float(rr[0]) + __uint_as_float(rr[1]); }
;   l_reg = l_reg * alpha + ps;
;     ...
;   PK4(p0, 0, pa0); PK4(p0, 8, pa1); PK4(p1, 0, pa2); PK4(p1, 8, pa3);
;     ...
; }
; __device__ __forceinline__ void qkt(f32x16& p0, f32x16& p1, const bf16_t* Ks, const bf16x8* qr, int r32, int hi) {
;   p0 = f32x16{}; p1 = f32x16{};
; #pragma unroll
;   for (int d0 = 0; d0 < 8; ++d0) { int cb = (d0 * 16 + hi * 8) * 2;
;     bf16x8 b0 = *reinterpret_cast<const bf16x8*>((const char*)Ks + KSWZ(r32, cb));
;     bf16x8 b1 = *reinterpret_cast<const bf16x8*>((const char*)Ks + KSWZ(32 + r32, cb));
;     p0 = __builtin_amdgcn_mfma_f32_32x32x16_bf16(b0, qr[d0], p0, 0, 0, 0);
;     p1 = __builtin_amdgcn_mfma_f32_32x32x16_bf16(b1, qr[d0], p1, 0, 0, 0); }
; }
; __device__ __forceinline__ int v_st(int k, int c) { const int kk = (k & ~0xC) | ((k & 4) << 1) | ((k & 8) >> 1); return ((kk >> 3) * 4 + (c >> 5)) * 512 + ((kk & 7) * 32 + (c & 31)) * 2; }
; __device__ __forceinline__ int v_rd_base(int lane) { return ((lane & 3) << 3) | (((lane >> 2) & 3) << 6) | (((lane >> 4) & 1) << 5) | (((lane >> 5) & 1) << 8); }
; template <int OFF> __device__ __forceinline__ s16x4 tr_read(int vb) {
;   s16x4 r; asm volatile("ds_read_b64_tr_b16 %0, %1 offset:%2" : "=&v"(r) : "v"(vb), "i"(OFF) : "memory"); return r;
; }
; template <int D0> __device__ __forceinline__ void pv_one(f32x16& od, int vb, bf16x8 pa0, bf16x8 pa1, bf16x8 pa2, bf16x8 pa3) {
;   const s16x4 l0 = tr_read<v_rd_off(D0, 0, 0)>(vb), h0 = tr_read<v_rd_off(D0, 0, 1)>(vb), l1 = tr_read<v_rd_off(D0, 1, 0)>(vb), h1 = tr_read<v_rd_off(D0, 1, 1)>(vb);
;   const s16x4 l2 = tr_read<v_rd_off(D0, 2, 0)>(vb), h2 = tr_read<v_rd_off(D0, 2, 1)>(vb), l3 = tr_read<v_rd_off(D0, 3, 0)>(vb), h3 = tr_read<v_rd_off(D0, 3, 1)>(vb);
;   asm volatile("s_waitcnt lgkmcnt(0)" ::: "memory"); SBAR();
;     ...
;   od = __builtin_amdgcn_mfma_f32_32x32x16_bf16(pa0, PK(l0, h0), od, 0, 0, 0);
.LBB0_70:
	ds_read_b128 v[64:67], v184 offset:49152
	ds_read_b128 v[68:71], v184 offset:57344
	s_waitcnt lgkmcnt(1)
	v_mfma_f32_32x32x16_bf16 v[80:95], v[64:67], v[126:129], 0
	s_waitcnt lgkmcnt(0)
	v_mfma_f32_32x32x16_bf16 v[64:79], v[68:71], v[126:129], 0
	ds_read_b128 v[126:129], v187 offset:49152
	s_waitcnt vmcnt(3)
	ds_read_b128 v[130:133], v187 offset:57344
	s_waitcnt lgkmcnt(1)
	v_mfma_f32_32x32x16_bf16 v[80:95], v[126:129], v[122:125], v[80:95]
	s_waitcnt lgkmcnt(0)
	v_mfma_f32_32x32x16_bf16 v[64:79], v[130:133], v[122:125], v[64:79]
	ds_read_b128 v[122:125], v185 offset:49152
	ds_read_b128 v[126:129], v185 offset:57344
	s_waitcnt lgkmcnt(1)
	v_mfma_f32_32x32x16_bf16 v[80:95], v[122:125], v[118:121], v[80:95]
	s_waitcnt lgkmcnt(0)
	v_mfma_f32_32x32x16_bf16 v[64:79], v[126:129], v[118:121], v[64:79]
	ds_read_b128 v[118:121], v186 offset:49152
	ds_read_b128 v[122:125], v186 offset:57344
	s_waitcnt lgkmcnt(1)
	v_mfma_f32_32x32x16_bf16 v[80:95], v[118:121], v[114:117], v[80:95]
	s_waitcnt lgkmcnt(0)
	v_mfma_f32_32x32x16_bf16 v[64:79], v[122:125], v[114:117], v[64:79]
	ds_read_b128 v[114:117], v188 offset:49152
	ds_read_b128 v[118:121], v188 offset:57344
	v_exp_f32_e32 v122, v152
	v_exp_f32_e32 v123, v153
	s_waitcnt lgkmcnt(1)
	v_mfma_f32_32x32x16_bf16 v[80:95], v[114:117], v[110:113], v[80:95]
	s_waitcnt lgkmcnt(0)
	v_mfma_f32_32x32x16_bf16 v[64:79], v[118:121], v[110:113], v[64:79]
	ds_read_b128 v[110:113], v189 offset:49152
	ds_read_b128 v[114:117], v189 offset:57344
	v_exp_f32_e32 v118, v160
	v_exp_f32_e32 v119, v161
	v_exp_f32_e32 v120, v154
	v_exp_f32_e32 v121, v155
	s_waitcnt lgkmcnt(1)
	v_mfma_f32_32x32x16_bf16 v[80:95], v[110:113], v[106:109], v[80:95]
	s_waitcnt lgkmcnt(0)
	v_mfma_f32_32x32x16_bf16 v[64:79], v[114:117], v[106:109], v[64:79]
	ds_read_b128 v[106:109], v190 offset:49152
	ds_read_b128 v[110:113], v190 offset:57344
	v_exp_f32_e32 v114, v148
	v_exp_f32_e32 v115, v149
	v_exp_f32_e32 v116, v146
	v_exp_f32_e32 v117, v147
	s_waitcnt lgkmcnt(1)
	v_mfma_f32_32x32x16_bf16 v[80:95], v[106:109], v[102:105], v[80:95]
	s_waitcnt lgkmcnt(0)
	v_mfma_f32_32x32x16_bf16 v[64:79], v[110:113], v[102:105], v[64:79]
	ds_read_b128 v[102:105], v191 offset:49152
	ds_read_b128 v[106:109], v191 offset:57344
	v_exp_f32_e32 v110, v156
	v_exp_f32_e32 v111, v157
	v_exp_f32_e32 v112, v150
	v_exp_f32_e32 v113, v151
	s_waitcnt lgkmcnt(1)
	v_mfma_f32_32x32x16_bf16 v[80:95], v[102:105], v[98:101], v[80:95]
	s_waitcnt lgkmcnt(0)
	v_mfma_f32_32x32x16_bf16 v[64:79], v[106:109], v[98:101], v[64:79]
	v_add_f32_e32 v98, 0, v206
	v_add_f32_e32 v98, v208, v98
	v_add_f32_e32 v98, v163, v98
	v_add_f32_e32 v98, v207, v98
	v_add_f32_e32 v98, v164, v98
	v_add_f32_e32 v98, v205, v98
	v_add_f32_e32 v98, v165, v98
	v_add_f32_e32 v98, v204, v98
	v_add_f32_e32 v98, v201, v98
	v_add_f32_e32 v98, v203, v98
	v_add_f32_e32 v98, v200, v98
	v_add_f32_e32 v98, v202, v98
	v_exp_f32_e32 v108, v158
	v_add_f32_e32 v98, v197, v98
	v_exp_f32_e32 v109, v159
	v_add_f32_e32 v98, v199, v98
	v_add_f32_e32 v98, v196, v98
	v_add_f32_e32 v98, v198, v98
	v_add_f32_e32 v98, v108, v98
	v_add_f32_e32 v98, v109, v98
	v_add_f32_e32 v98, v110, v98
	v_add_f32_e32 v98, v111, v98
	v_add_f32_e32 v98, v112, v98
	v_add_f32_e32 v98, v113, v98
	v_add_f32_e32 v98, v114, v98
	v_add_f32_e32 v98, v115, v98
	v_add_f32_e32 v98, v116, v98
	v_add_f32_e32 v98, v117, v98
	v_add_f32_e32 v98, v118, v98
	v_add_f32_e32 v98, v119, v98
	v_add_f32_e32 v98, v120, v98
	v_add_f32_e32 v98, v121, v98
	v_add_f32_e32 v98, v122, v98
	v_add_f32_e32 v98, v123, v98
	v_mov_b32_e32 v99, v98
	v_cvt_pk_bf16_f32 v100, v206, v208
	v_cvt_pk_bf16_f32 v101, v163, v207
	v_cvt_pk_bf16_f32 v102, v164, v205
	v_cvt_pk_bf16_f32 v103, v165, v204
	s_nop 1
	v_permlane32_swap_b32_e32 v98, v99
	v_permlane32_swap_b32_e32 v100, v102
	v_permlane32_swap_b32_e32 v101, v103
	v_cvt_pk_bf16_f32 v104, v201, v203
	v_cvt_pk_bf16_f32 v105, v200, v202
	v_cvt_pk_bf16_f32 v106, v197, v199
	v_cvt_pk_bf16_f32 v107, v196, v198
	v_cvt_pk_bf16_f32 v108, v108, v109
	v_cvt_pk_bf16_f32 v109, v110, v111
	v_cvt_pk_bf16_f32 v110, v112, v113
	v_cvt_pk_bf16_f32 v111, v114, v115
	v_cvt_pk_bf16_f32 v112, v116, v117
	v_cvt_pk_bf16_f32 v113, v118, v119
	v_cvt_pk_bf16_f32 v114, v120, v121
	v_cvt_pk_bf16_f32 v115, v122, v123
	s_nop 0
	v_permlane32_swap_b32_e32 v104, v106
	v_permlane32_swap_b32_e32 v105, v107
	v_permlane32_swap_b32_e32 v108, v110
	v_permlane32_swap_b32_e32 v109, v111
	v_permlane32_swap_b32_e32 v112, v114
	v_permlane32_swap_b32_e32 v113, v115
	ds_read_b64_tr_b16 v[116:117], v174 offset:0
	ds_read_b64_tr_b16 v[118:119], v174 offset:0x800
	ds_read_b64_tr_b16 v[120:121], v174 offset:0x1000
	ds_read_b64_tr_b16 v[122:123], v174 offset:0x1800
	ds_read_b64_tr_b16 v[124:125], v174 offset:0x2000
	ds_read_b64_tr_b16 v[126:127], v174 offset:0x2800
	ds_read_b64_tr_b16 v[128:129], v174 offset:0x3000
	ds_read_b64_tr_b16 v[130:131], v174 offset:0x3800
	s_waitcnt lgkmcnt(6)
	s_nop 0
	v_mfma_f32_32x32x16_bf16 v[0:15], v[100:103], v[116:119], v[0:15]
	ds_read_b64_tr_b16 v[116:117], v174 offset:0x200
	ds_read_b64_tr_b16 v[118:119], v174 offset:0xa00
	s_waitcnt lgkmcnt(6)
	v_mfma_f32_32x32x16_bf16 v[0:15], v[104:107], v[120:123], v[0:15]
	ds_read_b64_tr_b16 v[120:121], v174 offset:0x1200
	ds_read_b64_tr_b16 v[122:123], v174 offset:0x1a00
	s_waitcnt lgkmcnt(6)
	v_mfma_f32_32x32x16_bf16 v[0:15], v[108:111], v[124:127], v[0:15]
	ds_read_b64_tr_b16 v[124:125], v174 offset:0x2200
	ds_read_b64_tr_b16 v[126:127], v174 offset:0x2a00
	s_waitcnt lgkmcnt(6)
	v_mfma_f32_32x32x16_bf16 v[0:15], v[112:115], v[128:131], v[0:15]
	ds_read_b64_tr_b16 v[128:129], v174 offset:0x3200
	ds_read_b64_tr_b16 v[130:131], v174 offset:0x3a00
	s_waitcnt lgkmcnt(6)
; __device__ __forceinline__ void partialSM(f32x16& p0, f32x16& p1, float& m_reg, float& mn, float& alpha) {
; template <int OFF> __device__ __forceinline__ s16x4 tr_read(int vb) {
;   s16x4 r; asm volatile("ds_read_b64_tr_b16 %0, %1 offset:%2" : "=&v"(r) : "v"(vb), "i"(OFF) : "memory"); return r;
; }
; template <int D0> __device__ __forceinline__ void pv_one(f32x16& od, int vb, bf16x8 pa0, bf16x8 pa1, bf16x8 pa2, bf16x8 pa3) {
;   const s16x4 l0 = tr_read<v_rd_off(D0, 0, 0)>(vb), h0 = tr_read<v_rd_off(D0, 0, 1)>(vb), l1 = tr_read<v_rd_off(D0, 1, 0)>(vb), h1 = tr_read<v_rd_off(D0, 1, 1)>(vb);
;   const s16x4 l2 = tr_read<v_rd_off(D0, 2, 0)>(vb), h2 = tr_read<v_rd_off(D0, 2, 1)>(vb), l3 = tr_read<v_rd_off(D0, 3, 0)>(vb), h3 = tr_read<v_rd_off(D0, 3, 1)>(vb);
;   asm volatile("s_waitcnt lgkmcnt(0)" ::: "memory"); SBAR();
;     ...
;   od = __builtin_amdgcn_mfma_f32_32x32x16_bf16(pa0, PK(l0, h0), od, 0, 0, 0);
;   od = __builtin_amdgcn_mfma_f32_32x32x16_bf16(pa1, PK(l1, h1), od, 0, 0, 0);
;   od = __builtin_amdgcn_mfma_f32_32x32x16_bf16(pa2, PK(l2, h2), od, 0, 0, 0);
;   od = __builtin_amdgcn_mfma_f32_32x32x16_bf16(pa3, PK(l3, h3), od, 0, 0, 0);
;     ...
; }
; __device__ __forceinline__ void pv_d0(f32x16* o, int vb, bf16x8 pa0, bf16x8 pa1, bf16x8 pa2, bf16x8 pa3) {
;   pv_one<0>(o[0], vb, pa0, pa1, pa2, pa3); pv_one<1>(o[1], vb, pa0, pa1, pa2, pa3); pv_one<2>(o[2], vb, pa0, pa1, pa2, pa3); pv_one<3>(o[3], vb, pa0, pa1, pa2, pa3);
; }
; __device__ __forceinline__ void attn_dense_body(const bf16_t* __restrict__ Qb, const bf16_t* __restrict__ Kh, const bf16_t* __restrict__ Vh,
;                                                 bf16_t* __restrict__ Ob, int seq, char* lds, const Ctx& cx) {
;   const int tid = cx.tid_(), wid = tid >> 6, lane = tid & 63, r32 = lane & 31, hi = lane >> 5;
;   bf16_t* V_lds = (bf16_t*)lds; bf16_t* K_lds = (bf16_t*)(lds + 2 * SHM_V);
;   float* ws = (float*)(lds + 2 * SHM_V + 2 * SHM_K) + wid * 64; float* li_l = ws; float* al_l = ws + 32;
;   float m_reg = -1e30f, l_reg = 0; f32x16 o[4] = {}; bf16x8 qr[8];
;   const bf16_t* Qw = Qb + (long)(wid * QBLK + r32) * LDQ + hi * 8;
; #pragma unroll
;   for (int d0 = 0; d0 < 8; ++d0) qr[d0] = ld8(Qw + d0 * 16);
;   const int sr = tid >> 4, sc = (tid & 15) * 8, vst0 = v_st(sr, sc), vst1 = v_st(32 + sr, sc);
;   const int vb0 = (int)(uintptr_t)V_lds + v_rd_base(lane);
;   struct { bf16x8 vs0, vs1, ks0, ks1; } sr_[2];
	v_mfma_f32_32x32x16_bf16 v[48:63], v[100:103], v[116:119], v[48:63]
	ds_read_b64_tr_b16 v[116:117], v174 offset:0x400
	ds_read_b64_tr_b16 v[118:119], v174 offset:0xc00
	s_waitcnt lgkmcnt(6)
	v_mfma_f32_32x32x16_bf16 v[48:63], v[104:107], v[120:123], v[48:63]
	ds_read_b64_tr_b16 v[120:121], v174 offset:0x1400
	ds_read_b64_tr_b16 v[122:123], v174 offset:0x1c00
	s_waitcnt lgkmcnt(6)
	v_mfma_f32_32x32x16_bf16 v[48:63], v[108:111], v[124:127], v[48:63]
	ds_read_b64_tr_b16 v[124:125], v174 offset:0x2400
	ds_read_b64_tr_b16 v[126:127], v174 offset:0x2c00
	s_waitcnt lgkmcnt(6)
	v_mfma_f32_32x32x16_bf16 v[48:63], v[112:115], v[128:131], v[48:63]
	ds_read_b64_tr_b16 v[128:129], v174 offset:0x3400
	ds_read_b64_tr_b16 v[130:131], v174 offset:0x3c00
	s_waitcnt lgkmcnt(6)
	v_mfma_f32_32x32x16_bf16 v[32:47], v[100:103], v[116:119], v[32:47]
	ds_read_b64_tr_b16 v[116:117], v174 offset:0x600
	ds_read_b64_tr_b16 v[118:119], v174 offset:0xe00
	s_waitcnt lgkmcnt(6)
	v_mfma_f32_32x32x16_bf16 v[32:47], v[104:107], v[120:123], v[32:47]
	ds_read_b64_tr_b16 v[120:121], v174 offset:0x1600
	ds_read_b64_tr_b16 v[122:123], v174 offset:0x1e00
	s_waitcnt lgkmcnt(6)
	v_mfma_f32_32x32x16_bf16 v[32:47], v[108:111], v[124:127], v[32:47]
	ds_read_b64_tr_b16 v[124:125], v174 offset:0x2600
	ds_read_b64_tr_b16 v[126:127], v174 offset:0x2e00
	s_waitcnt lgkmcnt(6)
	v_mfma_f32_32x32x16_bf16 v[32:47], v[112:115], v[128:131], v[32:47]
	ds_read_b64_tr_b16 v[128:129], v174 offset:0x3600
	ds_read_b64_tr_b16 v[130:131], v174 offset:0x3e00
	s_waitcnt lgkmcnt(6)
	v_mfma_f32_32x32x16_bf16 v[16:31], v[100:103], v[116:119], v[16:31]
	v_max_f32_e32 v100, v81, v81
	v_max_f32_e32 v101, v80, v80
	v_max_f32_e32 v100, v101, v100
	v_max3_f32 v100, v100, v82, v83
	v_max3_f32 v100, v100, v84, v85
	v_max3_f32 v100, v100, v86, v87
	v_max3_f32 v100, v100, v88, v89
	v_max3_f32 v100, v100, v90, v91
	v_max3_f32 v100, v100, v92, v93
	s_waitcnt lgkmcnt(4)
	v_mfma_f32_32x32x16_bf16 v[16:31], v[104:107], v[120:123], v[16:31]
	v_max3_f32 v100, v100, v94, v95
	v_max3_f32 v100, v100, v64, v65
	v_max3_f32 v100, v100, v66, v67
	v_max3_f32 v100, v100, v68, v69
	v_max3_f32 v100, v100, v70, v71
	v_max3_f32 v100, v100, v72, v73
	v_max3_f32 v100, v100, v74, v75
	v_max3_f32 v100, v100, v76, v77
	s_waitcnt lgkmcnt(2)
	v_mfma_f32_32x32x16_bf16 v[16:31], v[108:111], v[124:127], v[16:31]
	v_max3_f32 v100, v100, v78, v79
	v_mov_b32_e32 v101, v100
	s_nop 1
	v_permlane32_swap_b32_e32 v100, v101
	v_max_f32_e32 v101, v101, v101
	v_max_f32_e32 v100, v100, v100
	v_max_f32_e32 v100, v100, v101
	v_sub_f32_e32 v101, v100, v193
	v_cmp_ge_f32_e32 vcc, s29, v101
	v_max_f32_e32 v101, v193, v193
	v_max_f32_e32 v101, v101, v100
	s_waitcnt lgkmcnt(0)
	v_mfma_f32_32x32x16_bf16 v[16:31], v[112:115], v[128:131], v[16:31]
	v_sub_f32_e32 v100, v193, v101
	v_mul_f32_e32 v100, 0x3e0293ee, v100
	v_exp_f32_e32 v100, v100
	s_cmp_eq_u64 vcc, exec
	s_cselect_b64 s[6:7], -1, 0
	v_cndmask_b32_e64 v100, v100, 1.0, s[6:7]
	v_cmp_gt_f32_e32 vcc, 1.0, v100
	s_barrier
	s_cbranch_vccz .LBB0_74
	s_and_saveexec_b64 s[14:15], s[4:5]
	ds_write_b32 v179, v100 offset:128
	s_or_b64 exec, exec, s[14:15]
	s_waitcnt lgkmcnt(0)
	v_add_u32_e32 v114, v167, v96
	ds_read_b128 v[102:105], v114 offset:224
	ds_read_b128 v[106:109], v114 offset:192
	ds_read_b128 v[110:113], v114 offset:160
	ds_read_b128 v[114:117], v114 offset:128
	s_waitcnt lgkmcnt(3)
	v_pk_mul_f32 v[12:13], v[12:13], v[102:103]
	s_waitcnt lgkmcnt(2)
	v_pk_mul_f32 v[8:9], v[8:9], v[106:107]
	s_waitcnt lgkmcnt(1)
	v_pk_mul_f32 v[4:5], v[4:5], v[110:111]
	v_pk_mul_f32 v[14:15], v[14:15], v[104:105]
	v_pk_mul_f32 v[10:11], v[10:11], v[108:109]
	v_pk_mul_f32 v[6:7], v[6:7], v[112:113]
	s_waitcnt lgkmcnt(0)
	v_pk_mul_f32 v[2:3], v[2:3], v[116:117]
	v_pk_mul_f32 v[0:1], v[0:1], v[114:115]
	v_pk_mul_f32 v[60:61], v[60:61], v[102:103]
	v_pk_mul_f32 v[56:57], v[56:57], v[106:107]
	v_pk_mul_f32 v[52:53], v[52:53], v[110:111]
	v_pk_mul_f32 v[62:63], v[62:63], v[104:105]
	v_pk_mul_f32 v[58:59], v[58:59], v[108:109]
	v_pk_mul_f32 v[54:55], v[54:55], v[112:113]
	v_pk_mul_f32 v[50:51], v[50:51], v[116:117]
	v_pk_mul_f32 v[48:49], v[48:49], v[114:115]
	v_pk_mul_f32 v[44:45], v[44:45], v[102:103]
	v_pk_mul_f32 v[40:41], v[40:41], v[106:107]
	v_pk_mul_f32 v[36:37], v[36:37], v[110:111]
	v_pk_mul_f32 v[46:47], v[46:47], v[104:105]
	v_pk_mul_f32 v[42:43], v[42:43], v[108:109]
	v_pk_mul_f32 v[38:39], v[38:39], v[112:113]
	v_pk_mul_f32 v[34:35], v[34:35], v[116:117]
	v_pk_mul_f32 v[32:33], v[32:33], v[114:115]
	v_pk_mul_f32 v[28:29], v[28:29], v[102:103]
	v_pk_mul_f32 v[24:25], v[24:25], v[106:107]
	v_pk_mul_f32 v[20:21], v[20:21], v[110:111]
	v_pk_mul_f32 v[30:31], v[30:31], v[104:105]
	v_pk_mul_f32 v[26:27], v[26:27], v[108:109]
	v_pk_mul_f32 v[22:23], v[22:23], v[112:113]
	v_pk_mul_f32 v[18:19], v[18:19], v[116:117]
	v_pk_mul_f32 v[16:17], v[16:17], v[114:115]
; __device__ __forceinline__ void finishSM(f32x16& p0, f32x16& p1, float alpha, float& l_reg, bf16x8& pa0, bf16x8& pa1, bf16x8& pa2, bf16x8& pa3) {
; #pragma unroll
;   for (int r = 0; r < 16; ++r) p1[r] = __builtin_amdgcn_exp2f(p1[r]);
;   float ps = 0;
; #pragma unroll
;   for (int r = 0; r < 16; ++r) ps += p0[r];
; #pragma unroll
;   for (int r = 0; r < 16; ++r) ps += p1[r];
;   { auto rr = __builtin_amdgcn_permlane32_swap(__float_as_uint(ps), __float_as_uint(ps), false, false);
;     ps = __uint_as_float(rr[0]) + __uint_as_float(rr[1]); }
;   l_reg = l_reg * alpha + ps;
;     ...
;   PK4(p0, 0, pa0); PK4(p0, 8, pa1); PK4(p1, 0, pa2); PK4(p1, 8, pa3);
;     ...
; }
; __device__ __forceinline__ void qkt(f32x16& p0, f32x16& p1, const bf16_t* Ks, const bf16x8* qr, int r32, int hi) {
;   p0 = f32x16{}; p1 = f32x16{};
; #pragma unroll
;   for (int d0 = 0; d0 < 8; ++d0) { int cb = (d0 * 16 + hi * 8) * 2;
;     bf16x8 b0 = *reinterpret_cast<const bf16x8*>((const char*)Ks + KSWZ(r32, cb));
;     bf16x8 b1 = *reinterpret_cast<const bf16x8*>((const char*)Ks + KSWZ(32 + r32, cb));
;     p0 = __builtin_amdgcn_mfma_f32_32x32x16_bf16(b0, qr[d0], p0, 0, 0, 0);
;     p1 = __builtin_amdgcn_mfma_f32_32x32x16_bf16(b1, qr[d0], p1, 0, 0, 0); }
; }
; __device__ __forceinline__ int v_st(int k, int c) { const int kk = (k & ~0xC) | ((k & 4) << 1) | ((k & 8) >> 1); return ((kk >> 3) * 4 + (c >> 5)) * 512 + ((kk & 7) * 32 + (c & 31)) * 2; }
; __device__ __forceinline__ int v_rd_base(int lane) { return ((lane & 3) << 3) | (((lane >> 2) & 3) << 6) | (((lane >> 4) & 1) << 5) | (((lane >> 5) & 1) << 8); }
; template <int OFF> __device__ __forceinline__ s16x4 tr_read(int vb) {
;   s16x4 r; asm volatile("ds_read_b64_tr_b16 %0, %1 offset:%2" : "=&v"(r) : "v"(vb), "i"(OFF) : "memory"); return r;
; }
; template <int D0> __device__ __forceinline__ void pv_one(f32x16& od, int vb, bf16x8 pa0, bf16x8 pa1, bf16x8 pa2, bf16x8 pa3) {
;   const s16x4 l0 = tr_read<v_rd_off(D0, 0, 0)>(vb), h0 = tr_read<v_rd_off(D0, 0, 1)>(vb), l1 = tr_read<v_rd_off(D0, 1, 0)>(vb), h1 = tr_read<v_rd_off(D0, 1, 1)>(vb);
;   const s16x4 l2 = tr_read<v_rd_off(D0, 2, 0)>(vb), h2 = tr_read<v_rd_off(D0, 2, 1)>(vb), l3 = tr_read<v_rd_off(D0, 3, 0)>(vb), h3 = tr_read<v_rd_off(D0, 3, 1)>(vb);
;   asm volatile("s_waitcnt lgkmcnt(0)" ::: "memory"); SBAR();
;     ...
;   od = __builtin_amdgcn_mfma_f32_32x32x16_bf16(pa0, PK(l0, h0), od, 0, 0, 0);
.LBB0_74:
	v_cndmask_b32_e64 v101, v101, v193, s[6:7]
	v_mul_f32_e32 v101, 0xbe0293ee, v101
	v_fmamk_f32 v80, v80, 0x3e0293ee, v101
	v_fmamk_f32 v81, v81, 0x3e0293ee, v101
	v_fmamk_f32 v102, v82, 0x3e0293ee, v101
	v_exp_f32_e32 v82, v80
	v_fmamk_f32 v103, v84, 0x3e0293ee, v101
	v_exp_f32_e32 v84, v81
	v_fmamk_f32 v83, v83, 0x3e0293ee, v101
	v_exp_f32_e32 v80, v102
	v_fmamk_f32 v64, v64, 0x3e0293ee, v101
	v_exp_f32_e32 v83, v83
	v_fmamk_f32 v104, v85, 0x3e0293ee, v101
	v_fmamk_f32 v113, v94, 0x3e0293ee, v101
	v_fmamk_f32 v94, v75, 0x3e0293ee, v101
	v_exp_f32_e32 v75, v103
	v_exp_f32_e32 v102, v64
	v_add_f32_e32 v64, 0, v82
	v_fmamk_f32 v105, v86, 0x3e0293ee, v101
	v_exp_f32_e32 v81, v104
	v_add_f32_e32 v64, v84, v64
	v_fmamk_f32 v106, v87, 0x3e0293ee, v101
	v_fmamk_f32 v112, v93, 0x3e0293ee, v101
	v_fmamk_f32 v93, v74, 0x3e0293ee, v101
	v_exp_f32_e32 v74, v105
	v_add_f32_e32 v64, v80, v64
	v_fmamk_f32 v107, v88, 0x3e0293ee, v101
	v_fmamk_f32 v114, v95, 0x3e0293ee, v101
	v_fmamk_f32 v95, v76, 0x3e0293ee, v101
	v_exp_f32_e32 v76, v106
	v_add_f32_e32 v64, v83, v64
	v_fmamk_f32 v108, v89, 0x3e0293ee, v101
	v_fmamk_f32 v109, v90, 0x3e0293ee, v101
	v_fmamk_f32 v90, v71, 0x3e0293ee, v101
	v_exp_f32_e32 v71, v107
	v_add_f32_e32 v64, v75, v64
	v_fmamk_f32 v111, v92, 0x3e0293ee, v101
	v_fmamk_f32 v92, v73, 0x3e0293ee, v101
	v_exp_f32_e32 v73, v108
	v_add_f32_e32 v64, v81, v64
	v_fmamk_f32 v110, v91, 0x3e0293ee, v101
	v_fmamk_f32 v88, v69, 0x3e0293ee, v101
	v_exp_f32_e32 v69, v109
	v_add_f32_e32 v64, v74, v64
	v_fmamk_f32 v91, v72, 0x3e0293ee, v101
	v_exp_f32_e32 v72, v110
	v_add_f32_e32 v64, v76, v64
	v_fmamk_f32 v86, v67, 0x3e0293ee, v101
	v_exp_f32_e32 v67, v111
	v_add_f32_e32 v64, v71, v64
	v_fmamk_f32 v89, v70, 0x3e0293ee, v101
	v_exp_f32_e32 v70, v112
	v_add_f32_e32 v64, v73, v64
	v_fmamk_f32 v85, v66, 0x3e0293ee, v101
	v_exp_f32_e32 v66, v113
	v_add_f32_e32 v64, v69, v64
	v_fmamk_f32 v87, v68, 0x3e0293ee, v101
	v_exp_f32_e32 v68, v114
	v_add_f32_e32 v64, v72, v64
	v_fmamk_f32 v65, v65, 0x3e0293ee, v101
	v_add_f32_e32 v64, v67, v64
	v_exp_f32_e32 v103, v65
	v_add_f32_e32 v64, v70, v64
	v_exp_f32_e32 v85, v85
	v_add_f32_e32 v64, v66, v64
	v_exp_f32_e32 v86, v86
	v_add_f32_e32 v64, v68, v64
	v_exp_f32_e32 v87, v87
	v_add_f32_e32 v64, v102, v64
	v_exp_f32_e32 v88, v88
	v_add_f32_e32 v64, v103, v64
	v_exp_f32_e32 v89, v89
	v_add_f32_e32 v64, v85, v64
	v_exp_f32_e32 v90, v90
	v_add_f32_e32 v64, v86, v64
	v_exp_f32_e32 v91, v91
	v_add_f32_e32 v64, v87, v64
	v_exp_f32_e32 v92, v92
	v_add_f32_e32 v64, v88, v64
	v_exp_f32_e32 v93, v93
	v_add_f32_e32 v64, v89, v64
	v_exp_f32_e32 v94, v94
	v_add_f32_e32 v64, v90, v64
	v_fmamk_f32 v77, v77, 0x3e0293ee, v101
	v_exp_f32_e32 v95, v95
	v_add_f32_e32 v64, v91, v64
	v_fmamk_f32 v78, v78, 0x3e0293ee, v101
	v_exp_f32_e32 v104, v77
	v_add_f32_e32 v64, v92, v64
	v_fmac_f32_e32 v101, 0x3e0293ee, v79
	v_exp_f32_e32 v105, v78
	v_add_f32_e32 v64, v93, v64
	v_exp_f32_e32 v101, v101
	v_add_f32_e32 v64, v94, v64
	v_add_f32_e32 v64, v95, v64
	v_add_f32_e32 v64, v104, v64
	v_add_f32_e32 v64, v105, v64
	v_add_f32_e32 v64, v101, v64
	v_mov_b32_e32 v65, v64
	s_nop 1
	v_permlane32_swap_b32_e32 v64, v65
	v_cvt_pk_bf16_f32 v78, v82, v84
	v_cvt_pk_bf16_f32 v79, v80, v83
	v_cvt_pk_bf16_f32 v80, v75, v81
	v_cvt_pk_bf16_f32 v81, v74, v76
	v_cvt_pk_bf16_f32 v74, v71, v73
	v_cvt_pk_bf16_f32 v75, v69, v72
	v_cvt_pk_bf16_f32 v76, v67, v70
	v_cvt_pk_bf16_f32 v77, v66, v68
	v_cvt_pk_bf16_f32 v66, v102, v103
	v_cvt_pk_bf16_f32 v67, v85, v86
	v_cvt_pk_bf16_f32 v68, v87, v88
	v_cvt_pk_bf16_f32 v69, v89, v90
	v_cvt_pk_bf16_f32 v70, v91, v92
	v_cvt_pk_bf16_f32 v71, v93, v94
	v_cvt_pk_bf16_f32 v72, v95, v104
	v_cvt_pk_bf16_f32 v73, v105, v101
	s_nop 0
	v_permlane32_swap_b32_e32 v78, v80
	v_permlane32_swap_b32_e32 v79, v81
	v_permlane32_swap_b32_e32 v74, v76
	v_permlane32_swap_b32_e32 v75, v77
	v_permlane32_swap_b32_e32 v66, v68
	v_permlane32_swap_b32_e32 v67, v69
	v_permlane32_swap_b32_e32 v70, v72
	v_permlane32_swap_b32_e32 v71, v73
	ds_read_b64_tr_b16 v[82:83], v182 offset:0
	ds_read_b64_tr_b16 v[84:85], v182 offset:0x800
	ds_read_b64_tr_b16 v[86:87], v182 offset:0x1000
	ds_read_b64_tr_b16 v[88:89], v182 offset:0x1800
	ds_read_b64_tr_b16 v[90:91], v182 offset:0x2000
	ds_read_b64_tr_b16 v[92:93], v182 offset:0x2800
	ds_read_b64_tr_b16 v[102:103], v182 offset:0x3000
	ds_read_b64_tr_b16 v[104:105], v182 offset:0x3800
	s_waitcnt lgkmcnt(6)
	s_nop 0
	v_mfma_f32_32x32x16_bf16 v[0:15], v[78:81], v[82:85], v[0:15]
	ds_read_b64_tr_b16 v[82:83], v182 offset:0x200
	ds_read_b64_tr_b16 v[84:85], v182 offset:0xa00
	s_waitcnt lgkmcnt(6)
	v_mfma_f32_32x32x16_bf16 v[0:15], v[74:77], v[86:89], v[0:15]
	ds_read_b64_tr_b16 v[86:87], v182 offset:0x1200
	ds_read_b64_tr_b16 v[88:89], v182 offset:0x1a00
	s_waitcnt lgkmcnt(6)
	v_mfma_f32_32x32x16_bf16 v[0:15], v[66:69], v[90:93], v[0:15]
	ds_read_b64_tr_b16 v[90:91], v182 offset:0x2200
	ds_read_b64_tr_b16 v[92:93], v182 offset:0x2a00
	s_waitcnt lgkmcnt(6)
	v_mfma_f32_32x32x16_bf16 v[0:15], v[70:73], v[102:105], v[0:15]
	ds_read_b64_tr_b16 v[102:103], v182 offset:0x3200
	ds_read_b64_tr_b16 v[104:105], v182 offset:0x3a00
	s_waitcnt lgkmcnt(6)
	v_mfma_f32_32x32x16_bf16 v[48:63], v[78:81], v[82:85], v[48:63]
	ds_read_b64_tr_b16 v[82:83], v182 offset:0x400
	ds_read_b64_tr_b16 v[84:85], v182 offset:0xc00
	s_waitcnt lgkmcnt(6)
	v_mfma_f32_32x32x16_bf16 v[48:63], v[74:77], v[86:89], v[48:63]
	ds_read_b64_tr_b16 v[86:87], v182 offset:0x1400
	ds_read_b64_tr_b16 v[88:89], v182 offset:0x1c00
	s_waitcnt lgkmcnt(6)
	v_mfma_f32_32x32x16_bf16 v[48:63], v[66:69], v[90:93], v[48:63]
	ds_read_b64_tr_b16 v[90:91], v182 offset:0x2400
	ds_read_b64_tr_b16 v[92:93], v182 offset:0x2c00
	s_waitcnt lgkmcnt(6)
	v_mfma_f32_32x32x16_bf16 v[48:63], v[70:73], v[102:105], v[48:63]
	ds_read_b64_tr_b16 v[102:103], v182 offset:0x3400
	ds_read_b64_tr_b16 v[104:105], v182 offset:0x3c00
	s_waitcnt lgkmcnt(6)
	v_mfma_f32_32x32x16_bf16 v[32:47], v[78:81], v[82:85], v[32:47]
	ds_read_b64_tr_b16 v[82:83], v182 offset:0x600
	ds_read_b64_tr_b16 v[84:85], v182 offset:0xe00
	s_waitcnt lgkmcnt(6)
	v_mfma_f32_32x32x16_bf16 v[32:47], v[74:77], v[86:89], v[32:47]
	ds_read_b64_tr_b16 v[86:87], v182 offset:0x1600
	ds_read_b64_tr_b16 v[88:89], v182 offset:0x1e00
	s_waitcnt lgkmcnt(6)
	v_mfma_f32_32x32x16_bf16 v[32:47], v[66:69], v[90:93], v[32:47]
	ds_read_b64_tr_b16 v[90:91], v182 offset:0x2600
	ds_read_b64_tr_b16 v[92:93], v182 offset:0x2e00
	s_waitcnt lgkmcnt(6)
	v_mfma_f32_32x32x16_bf16 v[32:47], v[70:73], v[102:105], v[32:47]
	ds_read_b64_tr_b16 v[102:103], v182 offset:0x3600
	ds_read_b64_tr_b16 v[104:105], v182 offset:0x3e00
	s_waitcnt lgkmcnt(6)
	v_mfma_f32_32x32x16_bf16 v[16:31], v[78:81], v[82:85], v[16:31]
	s_waitcnt lgkmcnt(4)
	v_mfma_f32_32x32x16_bf16 v[16:31], v[74:77], v[86:89], v[16:31]
	s_waitcnt lgkmcnt(2)
	v_mfma_f32_32x32x16_bf16 v[16:31], v[66:69], v[90:93], v[16:31]
	s_waitcnt lgkmcnt(0)
	v_mfma_f32_32x32x16_bf16 v[16:31], v[70:73], v[102:105], v[16:31]
	s_and_saveexec_b64 s[6:7], s[4:5]
	s_cbranch_execz .LBB0_51
; #define SBAR() __builtin_amdgcn_sched_barrier(0)
; __device__ __forceinline__ void attn_dense_body(const bf16_t* __restrict__ Qb, const bf16_t* __restrict__ Kh, const bf16_t* __restrict__ Vh,
;                                                 bf16_t* __restrict__ Ob, int seq, char* lds, const Ctx& cx) {
;     ...
;   finishSM(pB0, pB1, alB, l_reg, pa0, pa1, pa2, pa3); SBAR();
;   pv_d0(o, vb0 + (int)SHM_V, pa0, pa1, pa2, pa3);
;   if (hi == 0) li_l[r32] = l_reg; asm volatile("s_waitcnt lgkmcnt(0)" ::: "memory");
	v_add_f32_e32 v66, v98, v99
	v_fmac_f32_e32 v66, v181, v162
	v_add_f32_e32 v64, v64, v65
	v_fmac_f32_e32 v64, v66, v100
	ds_write_b32 v179, v64
	s_branch .LBB0_51

; __device__ __forceinline__ void gemm_phase(const Ctx& cx, LAS unsigned char* lds, const GemmDesc& g) {
;   const int tid = cx.tid_(), wid = __builtin_amdgcn_readfirstlane(tid >> 6), lane = tid & 63, wr = wid >> 2, wc = wid & 3, fr = lane & 15, fq = lane >> 4;
;   const int nt = g.nt, ksplit = g.ksplit; const bool perm = g.mode <= 2;
;   unsigned voffA[2], voffB[2];
; #pragma unroll
;   for (int i = 0; i < 2; ++i) { int R, C; stage_rc(tid * 16 + i * 8192, R, C); const int Rb = perm ? ((R & ~31) + perm32(R & 31)) : R;
;     voffA[i] = g.chunked ? (unsigned)((R >> 4) * 65536 + (R & 15) * 32 + (C >> 4) * 512 + (C & 15) * 2) : ((unsigned)R * g.rowStrideA + (unsigned)(C * 2)); voffB[i] = (unsigned)Rb * g.ldbBytes + (unsigned)(C * 2); }
.LBB0_331:
	s_mov_b32 s98, 0
	v_readlane_b32 s2, v254, 23
	v_mbcnt_lo_u32_b32 v9, -1, 0
	v_mbcnt_hi_u32_b32 v9, -1, v9
	s_and_b64 vcc, exec, s[0:1]
	s_nop 0
	v_add_u32_e32 v1, s2, v9
	v_ashrrev_i32_e32 v0, 31, v1
	v_lshrrev_b32_e32 v0, 26, v0
	v_readfirstlane_b32 s12, v1
	v_lshlrev_b32_e32 v3, 4, v1
	v_add_u32_e32 v0, v1, v0
	v_bfe_i32 v1, v1, 27, 1
	v_lshrrev_b32_e32 v1, 22, v1
	v_add_u32_e32 v1, v3, v1
	v_and_b32_e32 v1, 0xfffffc00, v1
	v_sub_u32_e32 v1, v3, v1
	v_lshrrev_b32_e32 v2, 4, v1
	v_bitop3_b32 v2, v2, v1, 32 bitop3:0x6c
	v_ashrrev_i32_e32 v4, 31, v2
	v_ashrrev_i32_e32 v0, 6, v0
	v_lshrrev_b32_e32 v4, 26, v4
	v_lshlrev_b32_e32 v1, 3, v0
	v_add_u32_e32 v4, v2, v4
	v_and_b32_e32 v1, -16, v1
	v_ashrrev_i32_e32 v5, 6, v4
	v_add_u32_e32 v4, v5, v1
	v_mov_b32_e32 v1, v4
	s_cbranch_vccz .LBB0_333
	v_lshlrev_b32_e32 v1, 1, v4
	v_lshrrev_b32_e32 v6, 2, v4
	v_and_b32_e32 v7, 3, v5
	s_movk_i32 s2, 0xffe0
	v_and_b32_e32 v1, 24, v1
	v_and_b32_e32 v6, 4, v6
	v_and_or_b32 v7, v4, s2, v7
	v_or3_b32 v1, v7, v6, v1

; __device__ __forceinline__ void gemm_phase(const Ctx& cx, LAS unsigned char* lds, const GemmDesc& g) {
;     ...
;   for (;;) {
;     const bool has_next = S.next(ui + 1, nxt);
;     const size_t naoff = has_next ? (size_t)nxt.pm * tstepA + (size_t)(nxt.pn >> g.pnShift) * g.pnStrideA : aoffu;
;     const char* nA1 = g.A + naoff; const char* nA2 = g.A2 + naoff; const char* nB = has_next ? g.Bt + (size_t)nxt.pn * tstepB : cB;
.LBB0_349:
	s_mov_b32 s98, 1
	s_mov_b64 s[4:5], 0

; #define PG8_STAGE(bufoff, gbase, voff) do { _Pragma("unroll") for (int _i = 0; _i < 2; ++_i) \
;     __builtin_amdgcn_global_load_lds((const unsigned*)((const char*)(gbase) + (voff)[_i]), (LAS unsigned*)(lds + (bufoff) + ldsw + _i * 8192), 16, 0, 0); } while (0)
; #define PG8_LDA(dst, b, h) do { _Pragma("unroll") for (int m = 0; m < 4; ++m) _Pragma("unroll") for (int k = 0; k < 2; ++k) dst[m][k] = *(const LAS bf16x8*)(lds + PG8_SA(b, h) + aoff + m * 2048 + k * 1024); } while (0)
; #define PG8_LDB(dst, b, h) do { _Pragma("unroll") for (int n = 0; n < 2; ++n) _Pragma("unroll") for (int k = 0; k < 2; ++k) dst[n][k] = *(const LAS bf16x8*)(lds + PG8_SB(b, h) + boff + n * 2048 + k * 1024); } while (0)
; #define PG8_MMA(ai, bj, At, Bt) do { __builtin_amdgcn_s_setprio(1); _Pragma("unroll") for (int m = 0; m < 4; ++m) _Pragma("unroll") for (int n = 0; n < 2; ++n) _Pragma("unroll") for (int k = 0; k < 2; ++k) \
;     acc[ai][bj][m][n] = __builtin_amdgcn_mfma_f32_16x16x32_bf16(Bt[n][k], At[m][k], acc[ai][bj][m][n], 0, 0, 0); __builtin_amdgcn_s_setprio(0); } while (0)
; #define PG8_WAIT_V(n) asm volatile("s_waitcnt vmcnt(" #n ")" ::: "memory")
; #define PG8_WAIT_L(n) asm volatile("s_waitcnt lgkmcnt(" #n ")" ::: "memory")
; #define PG8_BAR __builtin_amdgcn_s_barrier()
; __device__ __forceinline__ void gemm_phase(const Ctx& cx, LAS unsigned char* lds, const GemmDesc& g) {
;     ...
;     for (int t = 0; t < nt; t += 2) {
;       const bool last = (t == nt - 2);
;       const char* a1 = ktile_ptr(cA1, cA2, t + 1, ksplit, kstepA);
;       const char* a2 = last ? ktile_ptr(nA1, nA2, 0, ksplit, kstepA) : ktile_ptr(cA1, cA2, t + 2, ksplit, kstepA);
;       const char* a3 = last ? ktile_ptr(nA1, nA2, 1, ksplit, kstepA) : ktile_ptr(cA1, cA2, t + 3, ksplit, kstepA);
;       const char* b2 = last ? nB : cB + (size_t)(t + 2) * kstepB; const char* b3 = b2 + kstepB;
;       PG8_LDB(B0, 0, 0); PG8_LDB(B1, 0, 1); PG8_SCHED; PG8_LDA(At, 0, 0); PG8_STAGE(PG8_SA(1, 1), a1 + hstepA, voffA);
;       PG8_WAIT_V(8); PG8_WAIT_L(0); PG8_BAR; PG8_MMA(0, 0, At, B0); PG8_MMA(0, 1, At, B1); PG8_BAR; PG8_SCHED;
;       PG8_LDA(At, 0, 1); PG8_STAGE(PG8_SB(0, 0), b2, voffB); PG8_STAGE(PG8_SB(0, 1), b2 + hstepB, voffB); PG8_STAGE(PG8_SA(0, 0), a2, voffA);
;       PG8_WAIT_V(8); PG8_WAIT_L(0); PG8_BAR; PG8_MMA(1, 0, At, B0); PG8_MMA(1, 1, At, B1); PG8_BAR; PG8_SCHED;
.LBB0_358:
	s_add_i32 s7, s6, 1
	s_sub_i32 s14, s7, s41
	s_min_u32 s76, s7, s14
	s_cmp_lt_u32 s7, s41
	s_cselect_b32 s7, s9, s17
	s_cselect_b32 s54, s8, s16
	s_lshl_b64 s[14:15], s[76:77], s80
	s_add_u32 s55, s54, s14
	s_addc_u32 s73, s7, s15
	s_add_i32 s76, 0, 0x10000
	v_add_u32_e32 v96, s76, v252
	s_add_i32 vcc_lo, 0, 0x14000
	ds_read_b128 v[130:133], v96
	ds_read_b128 v[134:137], v96 offset:1024
	ds_read_b128 v[138:141], v96 offset:2048
	ds_read_b128 v[142:145], v96 offset:3072
	v_add_u32_e32 v96, vcc_lo, v252
	ds_read_b128 v[146:149], v96
	ds_read_b128 v[150:153], v96 offset:1024
	ds_read_b128 v[154:157], v96 offset:2048
	ds_read_b128 v[158:161], v96 offset:3072
	s_add_u32 s72, s55, s28
	s_addc_u32 s73, s73, s29
	v_lshl_add_u64 v[194:195], s[72:73], 0, v[210:211]
	s_add_i32 m0, s51, 0xc000
	ds_read_b128 v[162:165], v237
	ds_read_b128 v[166:169], v237 offset:1024
	ds_read_b128 v[170:173], v237 offset:2048
	ds_read_b128 v[174:177], v237 offset:3072
	ds_read_b128 v[178:181], v237 offset:4096
	ds_read_b128 v[182:185], v237 offset:5120
	ds_read_b128 v[186:189], v237 offset:6144
	ds_read_b128 v[190:193], v237 offset:7168
	global_load_lds_dwordx4 v[194:195], off
	v_lshl_add_u64 v[194:195], s[72:73], 0, v[212:213]
	s_add_i32 m0, s51, 0xe000
	s_nop 0
	global_load_lds_dwordx4 v[194:195], off
	s_waitcnt vmcnt(24)
	s_cmp_lg_u32 s98, 0
	s_cbranch_scc1 .Lrelax0
	s_waitcnt vmcnt(8)
.Lrelax0:
	s_waitcnt lgkmcnt(0)
	s_barrier
	s_setprio 1
	s_waitcnt lgkmcnt(0)
	v_mfma_f32_16x16x32_bf16 v[126:129], v[130:133], v[162:165], v[126:129]
	v_mfma_f32_16x16x32_bf16 v[126:129], v[134:137], v[166:169], v[126:129]
	s_add_i32 s54, s6, 2
	s_cmp_lt_u32 s54, s41
	v_mfma_f32_16x16x32_bf16 v[122:125], v[142:145], v[166:169], v[122:125]
	s_cselect_b64 s[14:15], -1, 0
	s_and_b64 s[58:59], s[14:15], exec
	v_mfma_f32_16x16x32_bf16 v[122:125], v[138:141], v[162:165], v[122:125]
	s_cselect_b32 s7, 0, s41
	s_sub_i32 s7, s6, s7
	v_mfma_f32_16x16x32_bf16 v[118:121], v[146:149], v[162:165], v[118:121]
	s_add_i32 s76, s7, 2
	s_and_b64 s[14:15], s[14:15], exec
	v_mfma_f32_16x16x32_bf16 v[118:121], v[150:153], v[166:169], v[118:121]
	s_cselect_b32 s7, s9, s17
	s_cselect_b32 s58, s8, s16
	v_mfma_f32_16x16x32_bf16 v[114:117], v[158:161], v[166:169], v[114:117]
	s_lshl_b64 s[14:15], s[76:77], s80
	s_add_u32 s72, s58, s14
	v_mfma_f32_16x16x32_bf16 v[114:117], v[154:157], v[162:165], v[114:117]
	s_addc_u32 s7, s7, s15
	s_add_i32 s14, s6, 3
	v_mfma_f32_16x16x32_bf16 v[98:101], v[154:157], v[170:173], v[98:101]
	s_cmp_lt_u32 s14, s41
	s_cselect_b64 s[14:15], -1, 0
	v_mfma_f32_16x16x32_bf16 v[98:101], v[158:161], v[174:177], v[98:101]
	s_and_b64 s[58:59], s[14:15], exec
	s_cselect_b32 s58, 0, s41
	v_mfma_f32_16x16x32_bf16 v[102:105], v[150:153], v[174:177], v[102:105]
	s_sub_i32 s58, s6, s58
	s_add_i32 s76, s58, 3
	v_mfma_f32_16x16x32_bf16 v[102:105], v[146:149], v[170:173], v[102:105]
	s_and_b64 s[14:15], s[14:15], exec
	s_cselect_b32 s58, s9, s17
	v_mfma_f32_16x16x32_bf16 v[106:109], v[138:141], v[170:173], v[106:109]
	s_cselect_b32 s59, s8, s16
	s_lshl_b64 s[14:15], s[76:77], s80
	v_mfma_f32_16x16x32_bf16 v[106:109], v[142:145], v[174:177], v[106:109]
	s_add_u32 s59, s59, s14
	s_addc_u32 s58, s58, s15
	v_mfma_f32_16x16x32_bf16 v[110:113], v[134:137], v[174:177], v[110:113]
	s_cmp_eq_u32 s39, s6
	s_cselect_b32 s15, s13, s7
	v_mfma_f32_16x16x32_bf16 v[110:113], v[130:133], v[170:173], v[110:113]
	s_cselect_b32 s14, s12, s72
	s_cselect_b32 s7, s21, s58
	v_mfma_f32_16x16x32_bf16 v[92:95], v[130:133], v[178:181], v[92:95]
	s_cselect_b32 s6, s20, s59
	s_cselect_b32 s59, s97, s53
	v_mfma_f32_16x16x32_bf16 v[92:95], v[134:137], v[182:185], v[92:95]
	s_cselect_b32 s58, s96, s52
	s_mov_b32 s76, 0x10000
	v_mfma_f32_16x16x32_bf16 v[88:91], v[142:145], v[182:185], v[88:91]
	v_mfma_f32_16x16x32_bf16 v[88:91], v[138:141], v[178:181], v[88:91]
	v_mfma_f32_16x16x32_bf16 v[84:87], v[146:149], v[178:181], v[84:87]
	v_mfma_f32_16x16x32_bf16 v[84:87], v[150:153], v[182:185], v[84:87]
	v_mfma_f32_16x16x32_bf16 v[80:83], v[158:161], v[182:185], v[80:83]
	v_mfma_f32_16x16x32_bf16 v[80:83], v[154:157], v[178:181], v[80:83]
	v_mfma_f32_16x16x32_bf16 v[64:67], v[154:157], v[186:189], v[64:67]
	v_mfma_f32_16x16x32_bf16 v[64:67], v[158:161], v[190:193], v[64:67]
	v_mfma_f32_16x16x32_bf16 v[68:71], v[150:153], v[190:193], v[68:71]
	v_mfma_f32_16x16x32_bf16 v[68:71], v[146:149], v[186:189], v[68:71]
	v_mfma_f32_16x16x32_bf16 v[72:75], v[138:141], v[186:189], v[72:75]
	v_mfma_f32_16x16x32_bf16 v[72:75], v[142:145], v[190:193], v[72:75]
	v_mfma_f32_16x16x32_bf16 v[76:79], v[134:137], v[190:193], v[76:79]
	v_mfma_f32_16x16x32_bf16 v[76:79], v[130:133], v[186:189], v[76:79]
	s_setprio 0
	s_barrier
	s_add_i32 s55, s76, s36
	v_lshl_add_u64 v[194:195], s[58:59], 0, v[216:217]
	s_mov_b32 m0, s55
	ds_read_b128 v[162:165], v237 offset:16384
	ds_read_b128 v[166:169], v237 offset:17408
	ds_read_b128 v[170:173], v237 offset:18432
	ds_read_b128 v[174:177], v237 offset:19456
	ds_read_b128 v[178:181], v237 offset:20480
	ds_read_b128 v[182:185], v237 offset:21504
	ds_read_b128 v[186:189], v237 offset:22528
	ds_read_b128 v[190:193], v237 offset:23552
	global_load_lds_dwordx4 v[194:195], off
	s_add_i32 m0, s55, 0x2000
	v_lshl_add_u64 v[196:197], s[58:59], 0, v[214:215]
	s_add_u32 s58, s58, s30
	s_addc_u32 s59, s59, s31
	s_add_i32 s55, vcc_lo, s36
	global_load_lds_dwordx4 v[196:197], off
	v_lshl_add_u64 v[198:199], s[58:59], 0, v[216:217]
	s_mov_b32 m0, s55
	v_lshl_add_u64 v[200:201], s[58:59], 0, v[214:215]
	global_load_lds_dwordx4 v[198:199], off
	s_add_i32 m0, s55, 0x2000
	v_lshl_add_u64 v[202:203], s[14:15], 0, v[210:211]
	global_load_lds_dwordx4 v[200:201], off
	s_mov_b32 m0, s51
	s_nop 0
	global_load_lds_dwordx4 v[202:203], off
	v_lshl_add_u64 v[202:203], s[14:15], 0, v[212:213]
	s_mov_b32 m0, s43
	s_nop 0
	global_load_lds_dwordx4 v[202:203], off
	s_waitcnt vmcnt(24)
	s_cmp_lg_u32 s98, 0
	s_cbranch_scc1 .Lrelax1
	s_waitcnt vmcnt(8)
; #define PG8_STAGE(bufoff, gbase, voff) do { _Pragma("unroll") for (int _i = 0; _i < 2; ++_i) \
;     __builtin_amdgcn_global_load_lds((const unsigned*)((const char*)(gbase) + (voff)[_i]), (LAS unsigned*)(lds + (bufoff) + ldsw + _i * 8192), 16, 0, 0); } while (0)
; #define PG8_LDA(dst, b, h) do { _Pragma("unroll") for (int m = 0; m < 4; ++m) _Pragma("unroll") for (int k = 0; k < 2; ++k) dst[m][k] = *(const LAS bf16x8*)(lds + PG8_SA(b, h) + aoff + m * 2048 + k * 1024); } while (0)
; #define PG8_LDB(dst, b, h) do { _Pragma("unroll") for (int n = 0; n < 2; ++n) _Pragma("unroll") for (int k = 0; k < 2; ++k) dst[n][k] = *(const LAS bf16x8*)(lds + PG8_SB(b, h) + boff + n * 2048 + k * 1024); } while (0)
; #define PG8_MMA(ai, bj, At, Bt) do { __builtin_amdgcn_s_setprio(1); _Pragma("unroll") for (int m = 0; m < 4; ++m) _Pragma("unroll") for (int n = 0; n < 2; ++n) _Pragma("unroll") for (int k = 0; k < 2; ++k) \
;     acc[ai][bj][m][n] = __builtin_amdgcn_mfma_f32_16x16x32_bf16(Bt[n][k], At[m][k], acc[ai][bj][m][n], 0, 0, 0); __builtin_amdgcn_s_setprio(0); } while (0)
; #define PG8_WAIT_V(n) asm volatile("s_waitcnt vmcnt(" #n ")" ::: "memory")
; #define PG8_WAIT_L(n) asm volatile("s_waitcnt lgkmcnt(" #n ")" ::: "memory")
; #define PG8_BAR __builtin_amdgcn_s_barrier()
; #define PG8_SCHED __builtin_amdgcn_sched_barrier(0)
; __device__ __forceinline__ void gemm_phase(const Ctx& cx, LAS unsigned char* lds, const GemmDesc& g) {
;     ...
;       PG8_WAIT_V(8); PG8_WAIT_L(0); PG8_BAR; PG8_MMA(1, 0, At, B0); PG8_MMA(1, 1, At, B1); PG8_BAR; PG8_SCHED;
;       PG8_LDB(B0, 1, 0); PG8_LDB(B1, 1, 1); PG8_SCHED; PG8_LDA(At, 1, 0); PG8_STAGE(PG8_SA(0, 1), a2 + hstepA, voffA);
;       PG8_WAIT_V(8); PG8_WAIT_L(0); PG8_BAR; PG8_MMA(0, 0, At, B0); PG8_MMA(0, 1, At, B1); PG8_BAR; PG8_SCHED;
.Lrelax1:
	s_mov_b32 s98, 0
	s_waitcnt lgkmcnt(0)
	s_barrier
	s_setprio 1
	s_waitcnt lgkmcnt(0)
	v_mfma_f32_16x16x32_bf16 v[60:63], v[130:133], v[162:165], v[60:63]
	v_mfma_f32_16x16x32_bf16 v[60:63], v[134:137], v[166:169], v[60:63]
	v_mfma_f32_16x16x32_bf16 v[56:59], v[142:145], v[166:169], v[56:59]
	v_mfma_f32_16x16x32_bf16 v[56:59], v[138:141], v[162:165], v[56:59]
	v_mfma_f32_16x16x32_bf16 v[52:55], v[146:149], v[162:165], v[52:55]
	v_mfma_f32_16x16x32_bf16 v[52:55], v[150:153], v[166:169], v[52:55]
	v_mfma_f32_16x16x32_bf16 v[48:51], v[158:161], v[166:169], v[48:51]
	v_mfma_f32_16x16x32_bf16 v[48:51], v[154:157], v[162:165], v[48:51]
	v_mfma_f32_16x16x32_bf16 v[32:35], v[154:157], v[170:173], v[32:35]
	v_mfma_f32_16x16x32_bf16 v[32:35], v[158:161], v[174:177], v[32:35]
	v_mfma_f32_16x16x32_bf16 v[36:39], v[150:153], v[174:177], v[36:39]
	v_mfma_f32_16x16x32_bf16 v[36:39], v[146:149], v[170:173], v[36:39]
	v_mfma_f32_16x16x32_bf16 v[40:43], v[138:141], v[170:173], v[40:43]
	v_mfma_f32_16x16x32_bf16 v[40:43], v[142:145], v[174:177], v[40:43]
	v_mfma_f32_16x16x32_bf16 v[44:47], v[134:137], v[174:177], v[44:47]
	v_mfma_f32_16x16x32_bf16 v[44:47], v[130:133], v[170:173], v[44:47]
	v_mfma_f32_16x16x32_bf16 v[28:31], v[130:133], v[178:181], v[28:31]
	v_mfma_f32_16x16x32_bf16 v[28:31], v[134:137], v[182:185], v[28:31]
	v_mfma_f32_16x16x32_bf16 v[24:27], v[142:145], v[182:185], v[24:27]
	v_mfma_f32_16x16x32_bf16 v[24:27], v[138:141], v[178:181], v[24:27]
	v_mfma_f32_16x16x32_bf16 v[20:23], v[146:149], v[178:181], v[20:23]
	v_mfma_f32_16x16x32_bf16 v[20:23], v[150:153], v[182:185], v[20:23]
	v_mfma_f32_16x16x32_bf16 v[16:19], v[158:161], v[182:185], v[16:19]
	v_mfma_f32_16x16x32_bf16 v[16:19], v[154:157], v[178:181], v[16:19]
	v_mfma_f32_16x16x32_bf16 v[0:3], v[154:157], v[186:189], v[0:3]
	v_mfma_f32_16x16x32_bf16 v[0:3], v[158:161], v[190:193], v[0:3]
	v_mfma_f32_16x16x32_bf16 v[4:7], v[150:153], v[190:193], v[4:7]
	v_mfma_f32_16x16x32_bf16 v[4:7], v[146:149], v[186:189], v[4:7]
	v_mfma_f32_16x16x32_bf16 v[8:11], v[138:141], v[186:189], v[8:11]
	v_mfma_f32_16x16x32_bf16 v[8:11], v[142:145], v[190:193], v[8:11]
	v_mfma_f32_16x16x32_bf16 v[12:15], v[134:137], v[190:193], v[12:15]
	v_mfma_f32_16x16x32_bf16 v[12:15], v[130:133], v[186:189], v[12:15]
	s_setprio 0
	s_barrier
	s_add_i32 s55, 0, 0x18000
	v_add_u32_e32 v96, s55, v252
	s_add_i32 s58, 0, 0x1c000
	ds_read_b128 v[130:133], v96
	ds_read_b128 v[134:137], v96 offset:1024
	ds_read_b128 v[138:141], v96 offset:2048
	ds_read_b128 v[142:145], v96 offset:3072
	v_add_u32_e32 v96, s58, v252
	ds_read_b128 v[146:149], v96
	ds_read_b128 v[150:153], v96 offset:1024
	ds_read_b128 v[154:157], v96 offset:2048
	ds_read_b128 v[158:161], v96 offset:3072
	s_add_u32 s14, s14, s28
	s_addc_u32 s15, s15, s29
	s_mov_b32 m0, s40
	v_lshl_add_u64 v[202:203], s[14:15], 0, v[210:211]
	ds_read_b128 v[162:165], v237 offset:32768
	ds_read_b128 v[166:169], v237 offset:33792
	ds_read_b128 v[170:173], v237 offset:34816
	ds_read_b128 v[174:177], v237 offset:35840
	ds_read_b128 v[178:181], v237 offset:36864
	ds_read_b128 v[182:185], v237 offset:37888
	ds_read_b128 v[186:189], v237 offset:38912
	ds_read_b128 v[190:193], v237 offset:39936
	global_load_lds_dwordx4 v[202:203], off
	v_lshl_add_u64 v[202:203], s[14:15], 0, v[212:213]
	s_mov_b32 m0, s37
	s_nop 0
	global_load_lds_dwordx4 v[202:203], off
	s_waitcnt vmcnt(8)
	s_waitcnt lgkmcnt(0)
	s_barrier
	s_setprio 1
	s_waitcnt lgkmcnt(0)
	v_mfma_f32_16x16x32_bf16 v[126:129], v[130:133], v[162:165], v[126:129]
	v_mfma_f32_16x16x32_bf16 v[126:129], v[134:137], v[166:169], v[126:129]
	v_mfma_f32_16x16x32_bf16 v[122:125], v[142:145], v[166:169], v[122:125]
	v_mfma_f32_16x16x32_bf16 v[122:125], v[138:141], v[162:165], v[122:125]
	v_mfma_f32_16x16x32_bf16 v[118:121], v[146:149], v[162:165], v[118:121]
	v_mfma_f32_16x16x32_bf16 v[118:121], v[150:153], v[166:169], v[118:121]
	v_mfma_f32_16x16x32_bf16 v[114:117], v[158:161], v[166:169], v[114:117]
	v_mfma_f32_16x16x32_bf16 v[114:117], v[154:157], v[162:165], v[114:117]
	v_mfma_f32_16x16x32_bf16 v[98:101], v[154:157], v[170:173], v[98:101]
	v_mfma_f32_16x16x32_bf16 v[98:101], v[158:161], v[174:177], v[98:101]
	v_mfma_f32_16x16x32_bf16 v[102:105], v[150:153], v[174:177], v[102:105]
	v_mfma_f32_16x16x32_bf16 v[102:105], v[146:149], v[170:173], v[102:105]
	v_mfma_f32_16x16x32_bf16 v[106:109], v[138:141], v[170:173], v[106:109]
	v_mfma_f32_16x16x32_bf16 v[106:109], v[142:145], v[174:177], v[106:109]
	v_mfma_f32_16x16x32_bf16 v[110:113], v[134:137], v[174:177], v[110:113]
	v_mfma_f32_16x16x32_bf16 v[110:113], v[130:133], v[170:173], v[110:113]
	v_mfma_f32_16x16x32_bf16 v[92:95], v[130:133], v[178:181], v[92:95]
	v_mfma_f32_16x16x32_bf16 v[92:95], v[134:137], v[182:185], v[92:95]
	v_mfma_f32_16x16x32_bf16 v[88:91], v[142:145], v[182:185], v[88:91]
	v_mfma_f32_16x16x32_bf16 v[88:91], v[138:141], v[178:181], v[88:91]
	v_mfma_f32_16x16x32_bf16 v[84:87], v[146:149], v[178:181], v[84:87]
	v_mfma_f32_16x16x32_bf16 v[84:87], v[150:153], v[182:185], v[84:87]
	v_mfma_f32_16x16x32_bf16 v[80:83], v[158:161], v[182:185], v[80:83]
	v_mfma_f32_16x16x32_bf16 v[80:83], v[154:157], v[178:181], v[80:83]
	v_mfma_f32_16x16x32_bf16 v[64:67], v[154:157], v[186:189], v[64:67]
	v_mfma_f32_16x16x32_bf16 v[64:67], v[158:161], v[190:193], v[64:67]
	v_mfma_f32_16x16x32_bf16 v[68:71], v[150:153], v[190:193], v[68:71]
	v_mfma_f32_16x16x32_bf16 v[68:71], v[146:149], v[186:189], v[68:71]
	v_mfma_f32_16x16x32_bf16 v[72:75], v[138:141], v[186:189], v[72:75]
	v_mfma_f32_16x16x32_bf16 v[72:75], v[142:145], v[190:193], v[72:75]
	v_mfma_f32_16x16x32_bf16 v[76:79], v[134:137], v[190:193], v[76:79]
	v_mfma_f32_16x16x32_bf16 v[76:79], v[130:133], v[186:189], v[76:79]
	s_setprio 0
	s_barrier
; #define PG8_STAGE(bufoff, gbase, voff) do { _Pragma("unroll") for (int _i = 0; _i < 2; ++_i) \
;     __builtin_amdgcn_global_load_lds((const unsigned*)((const char*)(gbase) + (voff)[_i]), (LAS unsigned*)(lds + (bufoff) + ldsw + _i * 8192), 16, 0, 0); } while (0)
; #define PG8_LDA(dst, b, h) do { _Pragma("unroll") for (int m = 0; m < 4; ++m) _Pragma("unroll") for (int k = 0; k < 2; ++k) dst[m][k] = *(const LAS bf16x8*)(lds + PG8_SA(b, h) + aoff + m * 2048 + k * 1024); } while (0)
; #define PG8_MMA(ai, bj, At, Bt) do { __builtin_amdgcn_s_setprio(1); _Pragma("unroll") for (int m = 0; m < 4; ++m) _Pragma("unroll") for (int n = 0; n < 2; ++n) _Pragma("unroll") for (int k = 0; k < 2; ++k) \
;     acc[ai][bj][m][n] = __builtin_amdgcn_mfma_f32_16x16x32_bf16(Bt[n][k], At[m][k], acc[ai][bj][m][n], 0, 0, 0); __builtin_amdgcn_s_setprio(0); } while (0)
; #define PG8_WAIT_V(n) asm volatile("s_waitcnt vmcnt(" #n ")" ::: "memory")
; #define PG8_WAIT_L(n) asm volatile("s_waitcnt lgkmcnt(" #n ")" ::: "memory")
; #define PG8_BAR __builtin_amdgcn_s_barrier()
; #define PG8_SCHED __builtin_amdgcn_sched_barrier(0)
; __device__ __forceinline__ void gemm_phase(const Ctx& cx, LAS unsigned char* lds, const GemmDesc& g) {
;     ...
;       PG8_LDA(At, 1, 1); PG8_STAGE(PG8_SB(1, 0), b3, voffB); PG8_STAGE(PG8_SB(1, 1), b3 + hstepB, voffB); PG8_STAGE(PG8_SA(1, 0), a3, voffA);
;       PG8_WAIT_V(8); PG8_WAIT_L(0); PG8_BAR; PG8_MMA(1, 0, At, B0); PG8_MMA(1, 1, At, B1); PG8_BAR; PG8_SCHED;
;     }
;     if (wr == 0) PG8_BAR;
	s_add_i32 s14, s55, s36
	v_lshl_add_u64 v[194:195], v[194:195], 0, s[92:93]
	s_mov_b32 m0, s14
	ds_read_b128 v[162:165], v237 offset:49152
	ds_read_b128 v[166:169], v237 offset:50176
	ds_read_b128 v[170:173], v237 offset:51200
	ds_read_b128 v[174:177], v237 offset:52224
	ds_read_b128 v[178:181], v237 offset:53248
	ds_read_b128 v[182:185], v237 offset:54272
	ds_read_b128 v[186:189], v237 offset:55296
	ds_read_b128 v[190:193], v237 offset:56320
	global_load_lds_dwordx4 v[194:195], off
	v_lshl_add_u64 v[194:195], v[196:197], 0, s[92:93]
	s_add_i32 m0, s14, 0x2000
	s_add_i32 s14, s58, s36
	global_load_lds_dwordx4 v[194:195], off
	v_lshl_add_u64 v[194:195], v[198:199], 0, s[92:93]
	s_mov_b32 m0, s14
	s_nop 0
	global_load_lds_dwordx4 v[194:195], off
	v_lshl_add_u64 v[194:195], v[200:201], 0, s[92:93]
	s_add_i32 m0, s14, 0x2000
	s_nop 0
	global_load_lds_dwordx4 v[194:195], off
	v_lshl_add_u64 v[194:195], s[6:7], 0, v[210:211]
	s_mov_b32 m0, s0
	s_nop 0
	global_load_lds_dwordx4 v[194:195], off
	v_lshl_add_u64 v[194:195], s[6:7], 0, v[212:213]
	s_mov_b32 m0, s1
	s_nop 0
	global_load_lds_dwordx4 v[194:195], off
	s_waitcnt vmcnt(8)
	s_waitcnt lgkmcnt(0)
	s_barrier
	s_setprio 1
	s_waitcnt lgkmcnt(0)
	v_mfma_f32_16x16x32_bf16 v[60:63], v[130:133], v[162:165], v[60:63]
	v_mfma_f32_16x16x32_bf16 v[60:63], v[134:137], v[166:169], v[60:63]
	v_mfma_f32_16x16x32_bf16 v[56:59], v[142:145], v[166:169], v[56:59]
	v_mfma_f32_16x16x32_bf16 v[56:59], v[138:141], v[162:165], v[56:59]
	v_mfma_f32_16x16x32_bf16 v[52:55], v[146:149], v[162:165], v[52:55]
	v_mfma_f32_16x16x32_bf16 v[52:55], v[150:153], v[166:169], v[52:55]
	v_mfma_f32_16x16x32_bf16 v[48:51], v[158:161], v[166:169], v[48:51]
	v_mfma_f32_16x16x32_bf16 v[48:51], v[154:157], v[162:165], v[48:51]
	v_mfma_f32_16x16x32_bf16 v[32:35], v[154:157], v[170:173], v[32:35]
	v_mfma_f32_16x16x32_bf16 v[32:35], v[158:161], v[174:177], v[32:35]
	v_mfma_f32_16x16x32_bf16 v[36:39], v[150:153], v[174:177], v[36:39]
	v_mfma_f32_16x16x32_bf16 v[36:39], v[146:149], v[170:173], v[36:39]
	v_mfma_f32_16x16x32_bf16 v[40:43], v[138:141], v[170:173], v[40:43]
	v_mfma_f32_16x16x32_bf16 v[40:43], v[142:145], v[174:177], v[40:43]
	v_mfma_f32_16x16x32_bf16 v[44:47], v[134:137], v[174:177], v[44:47]
	v_mfma_f32_16x16x32_bf16 v[44:47], v[130:133], v[170:173], v[44:47]
	v_mfma_f32_16x16x32_bf16 v[28:31], v[130:133], v[178:181], v[28:31]
	v_mfma_f32_16x16x32_bf16 v[28:31], v[134:137], v[182:185], v[28:31]
	v_mfma_f32_16x16x32_bf16 v[24:27], v[142:145], v[182:185], v[24:27]
	v_mfma_f32_16x16x32_bf16 v[24:27], v[138:141], v[178:181], v[24:27]
	v_mfma_f32_16x16x32_bf16 v[20:23], v[146:149], v[178:181], v[20:23]
	v_mfma_f32_16x16x32_bf16 v[20:23], v[150:153], v[182:185], v[20:23]
	v_mfma_f32_16x16x32_bf16 v[16:19], v[158:161], v[182:185], v[16:19]
	v_mfma_f32_16x16x32_bf16 v[16:19], v[154:157], v[178:181], v[16:19]
	v_mfma_f32_16x16x32_bf16 v[0:3], v[154:157], v[186:189], v[0:3]
	v_mfma_f32_16x16x32_bf16 v[0:3], v[158:161], v[190:193], v[0:3]
	v_mfma_f32_16x16x32_bf16 v[4:7], v[150:153], v[190:193], v[4:7]
	v_mfma_f32_16x16x32_bf16 v[4:7], v[146:149], v[186:189], v[4:7]
	v_mfma_f32_16x16x32_bf16 v[8:11], v[138:141], v[186:189], v[8:11]
	v_mfma_f32_16x16x32_bf16 v[8:11], v[142:145], v[190:193], v[8:11]
	v_mfma_f32_16x16x32_bf16 v[12:15], v[134:137], v[190:193], v[12:15]
	v_mfma_f32_16x16x32_bf16 v[12:15], v[130:133], v[186:189], v[12:15]
	s_setprio 0
	s_barrier
	s_add_u32 s52, s52, 0x100
	s_addc_u32 s53, s53, 0
	s_cmp_ge_u32 s54, s10
	s_mov_b32 s6, s54
	s_cbranch_scc0 .LBB0_358
	v_readlane_b32 s6, v255, 19
	v_readlane_b32 s7, v255, 20
	s_and_b64 vcc, exec, s[6:7]
	s_cbranch_vccz .LBB0_361
	s_barrier

; #define LAS __attribute__((address_space(3)))
; __device__ __forceinline__ unsigned xb_add(unsigned* p, unsigned v) { return __hip_atomic_fetch_add(p, v, __ATOMIC_RELAXED, __HIP_MEMORY_SCOPE_AGENT); }
; __device__ __forceinline__ unsigned xb_xcc_id() { return (unsigned)__builtin_amdgcn_s_getreg((3 << 11) | 20) & 0xFu; }
; __global__ void __launch_bounds__(512) fwd_megakernel(Params p_unused) {
;   extern __shared__ __attribute__((aligned(16))) unsigned char lds[];
;   cg::grid_group grid = cg::this_grid();
;   const int wave0 = __builtin_amdgcn_readfirstlane((int)threadIdx.x >> 6);
;   { volatile LAS unsigned* st0 = (volatile LAS unsigned*)((LAS unsigned char*)lds + 128 * 1024);
;     if (threadIdx.x < 4) st0[threadIdx.x] = 0u;
;     __syncthreads();
;     KargP pq = (KargP)__builtin_amdgcn_kernarg_segment_ptr();
;     if (threadIdx.x == 0) (void)xb_add(&((unsigned*)(pq->ws + WS_BAR))[XB_XCNT(xb_xcc_id())], 1u); }
;   for (int s = 0; s < NSTEPS; ++s) {
;     int type, layer; step_info(s, type, layer);
;     KargP pp = (KargP)__builtin_amdgcn_kernarg_segment_ptr();
;     asm volatile("" : "+s"(pp));
;     Ctx cx; { int b_ = (int)blockIdx.x, g_ = (int)gridDim.x; asm volatile("" : "+s"(b_)); asm volatile("" : "+s"(g_)); cx.wave0 = wave0; cx.bid = b_; cx.G = g_; }
;     ...
;     const Params p = *pp;
;     ...
;     const Params p = p_unused;
;     ...
;     run_step(cx, p, type, layer, lds, false);
;     if (s + 1 < NSTEPS) {
;       if (p.ws == nullptr) grid.sync();
;       else { xcd_barrier(cx, (unsigned*)(p.ws + WS_BAR), (volatile LAS unsigned*)((LAS unsigned char*)lds + 128 * 1024)); }
;     }
;   }
; }
	.amdhsa_kernel _Z14fwd_megakernel6Params
		.amdhsa_group_segment_fixed_size 0
		.amdhsa_private_segment_fixed_size 0
		.amdhsa_kernarg_size 464
		.amdhsa_user_sgpr_count 2
		.amdhsa_user_sgpr_dispatch_ptr 0
		.amdhsa_user_sgpr_queue_ptr 0
		.amdhsa_user_sgpr_kernarg_segment_ptr 1
		.amdhsa_user_sgpr_dispatch_id 0
		.amdhsa_user_sgpr_kernarg_preload_length 0
		.amdhsa_user_sgpr_kernarg_preload_offset 0
		.amdhsa_user_sgpr_private_segment_size 0
		.amdhsa_uses_dynamic_stack 0
		.amdhsa_enable_private_segment 0
		.amdhsa_system_sgpr_workgroup_id_x 1
		.amdhsa_system_sgpr_workgroup_id_y 0
		.amdhsa_system_sgpr_workgroup_id_z 0
		.amdhsa_system_sgpr_workgroup_info 0
		.amdhsa_system_vgpr_workitem_id 2
		.amdhsa_next_free_vgpr 256
		.amdhsa_next_free_sgpr 100
		.amdhsa_accum_offset 256
		.amdhsa_reserve_vcc 1
		.amdhsa_float_round_mode_32 0
		.amdhsa_float_round_mode_16_64 0
		.amdhsa_float_denorm_mode_32 3
		.amdhsa_float_denorm_mode_16_64 3
		.amdhsa_dx10_clamp 1
		.amdhsa_ieee_mode 1
		.amdhsa_fp16_overflow 0
		.amdhsa_tg_split 0
		.amdhsa_exception_fp_ieee_invalid_op 0
		.amdhsa_exception_fp_denorm_src 0
		.amdhsa_exception_fp_ieee_div_zero 0
		.amdhsa_exception_fp_ieee_overflow 0
		.amdhsa_exception_fp_ieee_underflow 0
		.amdhsa_exception_fp_ieee_inexact 0
		.amdhsa_exception_int_div_zero 0
	.end_amdhsa_kernel

; __global__ void __launch_bounds__(512) fwd_megakernel(Params p_unused) {
;   extern __shared__ __attribute__((aligned(16))) unsigned char lds[];
amdhsa.kernels:
  - .agpr_count:     0
    .args:
      - .offset:         0
        .size:           208
        .value_kind:     by_value
      - .offset:         208
        .size:           4
        .value_kind:     hidden_block_count_x
      - .offset:         212
        .size:           4
        .value_kind:     hidden_block_count_y
      - .offset:         216
        .size:           4
        .value_kind:     hidden_block_count_z
      - .offset:         220
        .size:           2
        .value_kind:     hidden_group_size_x
      - .offset:         222
        .size:           2
        .value_kind:     hidden_group_size_y
      - .offset:         224
        .size:           2
        .value_kind:     hidden_group_size_z
      - .offset:         226
        .size:           2
        .value_kind:     hidden_remainder_x
      - .offset:         228
        .size:           2
        .value_kind:     hidden_remainder_y
      - .offset:         230
        .size:           2
        .value_kind:     hidden_remainder_z
      - .offset:         248
        .size:           8
        .value_kind:     hidden_global_offset_x
      - .offset:         256
        .size:           8
        .value_kind:     hidden_global_offset_y
      - .offset:         264
        .size:           8
        .value_kind:     hidden_global_offset_z
      - .offset:         272
        .size:           2
        .value_kind:     hidden_grid_dims
      - .offset:         296
        .size:           8
        .value_kind:     hidden_multigrid_sync_arg
      - .offset:         328
        .size:           4
        .value_kind:     hidden_dynamic_lds_size
    .group_segment_fixed_size: 0
    .kernarg_segment_align: 8
    .kernarg_segment_size: 464
    .language:       OpenCL C
    .language_version:
      - 2
      - 0
    .max_flat_workgroup_size: 512
    .name:           _Z14fwd_megakernel6Params
    .private_segment_fixed_size: 0
    .sgpr_count:     106
    .sgpr_spill_count: 153
    .symbol:         _Z14fwd_megakernel6Params.kd
    .uniform_work_group_size: 1
    .uses_dynamic_stack: false
    .vgpr_count:     256
    .vgpr_spill_count: 0
    .wavefront_size: 64
